# v40 + static priority raise for the trailing half (waves 4-7) through the epilogue and next unit head
# speedup vs baseline: 1.0076x; 1.0076x over previous
; #define PG8_STAGE(bufoff, gbase, voff) do { _Pragma("unroll") for (int _i = 0; _i < 2; ++_i) \
;         __builtin_amdgcn_global_load_lds((const unsigned*)((const char*)(gbase) + (voff)[_i]), (PG8_LAS unsigned*)(lds + (bufoff) + ldsw + _i * 8192), 16, 0, 0); } while (0)
; #define PG8_LDA(dst, b, h) do { _Pragma("unroll") for (int m = 0; m < 4; ++m) _Pragma("unroll") for (int k = 0; k < 2; ++k) dst[m][k] = *(const PG8_LAS bf16x8*)(lds + PG8_SA(b, h) + aoff + m * 2048 + k * 1024); } while (0)
; #define PG8_LDB(dst, b, h) do { _Pragma("unroll") for (int n = 0; n < 2; ++n) _Pragma("unroll") for (int k = 0; k < 2; ++k) dst[n][k] = *(const PG8_LAS bf16x8*)(lds + PG8_SB(b, h) + boff + n * 2048 + k * 1024); } while (0)
; #define PG8_MMA(ai, bj, At, Bt) do { __builtin_amdgcn_s_setprio(1); _Pragma("unroll") for (int m = 0; m < 4; ++m) _Pragma("unroll") for (int n = 0; n < 2; ++n) _Pragma("unroll") for (int k = 0; k < 2; ++k) \
;         acc[ai][bj][m][n] = __builtin_amdgcn_mfma_f32_16x16x32_bf16(Bt[n][k], At[m][k], acc[ai][bj][m][n], 0, 0, 0); __builtin_amdgcn_s_setprio(0); } while (0)
; #define PG8_WAIT_V(n) asm volatile("s_waitcnt vmcnt(" #n ")" ::: "memory")
; #define PG8_WAIT_L(n) asm volatile("s_waitcnt lgkmcnt(" #n ")" ::: "memory")
; #define PG8_BAR __builtin_amdgcn_s_barrier()
; #define PG8_SCHED __builtin_amdgcn_sched_barrier(0)
; template <class Epi, class Sched, bool ALIGN_EPI = false, bool SP2 = false>
; __device__ __forceinline__ void gemm_phase(PG8_LAS unsigned char* lds, const Gemm g, const Sched& S, const Epi& E, int tid_in) {
;     ...
;             PG8_LDB(B0, 0, 0); PG8_LDB(B1, 0, 1); PG8_SCHED; PG8_LDA(At, 0, 0); PG8_STAGE(PG8_SA(1, 1), a1 + hstep, voffA);
;             PG8_WAIT_V(8); PG8_WAIT_L(0); PG8_BAR; PG8_MMA(0, 0, At, B0); PG8_MMA(0, 1, At, B1); PG8_BAR; PG8_SCHED;
;             PG8_LDA(At, 0, 1); PG8_STAGE(PG8_SB(0, 0), b2, voffB); PG8_STAGE(PG8_SB(0, 1), b2 + hstep, voffB); PG8_STAGE(PG8_SA(0, 0), a2, voffA);
;             PG8_WAIT_V(8); PG8_WAIT_L(0); PG8_BAR; PG8_MMA(1, 0, At, B0); PG8_MMA(1, 1, At, B1); PG8_BAR; PG8_SCHED;
.LBB0_158:
	v_or_b32_e32 v32, 0x10000, v194
	v_add_u32_e32 v36, 0x10400, v194
	v_add_u32_e32 v44, 0x10800, v194
	v_add_u32_e32 v48, 0x10c00, v194
	v_or_b32_e32 v81, 0x14000, v194
	v_add_u32_e32 v162, 0x14400, v194
	ds_read_b128 v[32:35], v32
	ds_read_b128 v[36:39], v36
	ds_read_b128 v[44:47], v44
	ds_read_b128 v[48:51], v48
	ds_read_b128 v[158:161], v81
	ds_read_b128 v[162:165], v162
	v_add_u32_e32 v81, 0x14800, v194
	v_add_u32_e32 v170, 0x14c00, v194
	ds_read_b128 v[166:169], v81
	ds_read_b128 v[170:173], v170
	s_add_u32 s29, s84, 0xfffc0080
	s_addc_u32 s31, s85, -1
	s_cmp_eq_u32 s27, 12
	s_cselect_b32 s89, s21, s31
	s_cselect_b32 s88, s22, s29
	s_cselect_b32 s87, s23, s26
	s_cselect_b32 s86, s24, s25
	s_mov_b32 m0, s63
	v_lshl_add_u64 v[174:175], s[84:85], 0, v[154:155]
	ds_read_b128 v[182:185], v177
	ds_read_b128 v[200:203], v177 offset:1024
	ds_read_b128 v[204:207], v177 offset:2048
	ds_read_b128 v[208:211], v177 offset:3072
	ds_read_b128 v[212:215], v177 offset:4096
	ds_read_b128 v[216:219], v177 offset:5120
	ds_read_b128 v[226:229], v177 offset:6144
	ds_read_b128 v[232:235], v177 offset:7168
	global_load_lds_dwordx4 v[174:175], off
	v_lshl_add_u64 v[174:175], s[84:85], 0, v[156:157]
	s_mov_b32 m0, s62
	s_nop 0
	global_load_lds_dwordx4 v[174:175], off
	s_waitcnt vmcnt(8)
	s_waitcnt lgkmcnt(0)
	s_barrier
	s_setprio 1
	s_waitcnt lgkmcnt(0)
	v_mfma_f32_16x16x32_bf16 v[142:145], v[32:35], v[182:185], v[142:145]
	v_mfma_f32_16x16x32_bf16 v[138:141], v[44:47], v[182:185], v[138:141]
	v_mfma_f32_16x16x32_bf16 v[126:129], v[32:35], v[204:207], v[126:129]
	v_mfma_f32_16x16x32_bf16 v[122:125], v[44:47], v[204:207], v[122:125]
	v_mfma_f32_16x16x32_bf16 v[110:113], v[32:35], v[212:215], v[110:113]
	v_mfma_f32_16x16x32_bf16 v[106:109], v[44:47], v[212:215], v[106:109]
	v_mfma_f32_16x16x32_bf16 v[94:97], v[32:35], v[226:229], v[94:97]
	v_mfma_f32_16x16x32_bf16 v[90:93], v[44:47], v[226:229], v[90:93]
	v_mfma_f32_16x16x32_bf16 v[142:145], v[36:39], v[200:203], v[142:145]
	v_mfma_f32_16x16x32_bf16 v[138:141], v[48:51], v[200:203], v[138:141]
	v_mfma_f32_16x16x32_bf16 v[126:129], v[36:39], v[208:211], v[126:129]
	v_mfma_f32_16x16x32_bf16 v[122:125], v[48:51], v[208:211], v[122:125]
	v_mfma_f32_16x16x32_bf16 v[110:113], v[36:39], v[216:219], v[110:113]
	v_mfma_f32_16x16x32_bf16 v[106:109], v[48:51], v[216:219], v[106:109]
	v_mfma_f32_16x16x32_bf16 v[94:97], v[36:39], v[232:235], v[94:97]
	v_mfma_f32_16x16x32_bf16 v[90:93], v[48:51], v[232:235], v[90:93]
	s_setprio 0
	s_setprio 1
	v_mfma_f32_16x16x32_bf16 v[134:137], v[158:161], v[182:185], v[134:137]
	v_mfma_f32_16x16x32_bf16 v[130:133], v[166:169], v[182:185], v[130:133]
	v_mfma_f32_16x16x32_bf16 v[118:121], v[158:161], v[204:207], v[118:121]
	v_mfma_f32_16x16x32_bf16 v[114:117], v[166:169], v[204:207], v[114:117]
	v_mfma_f32_16x16x32_bf16 v[102:105], v[158:161], v[212:215], v[102:105]
	v_mfma_f32_16x16x32_bf16 v[98:101], v[166:169], v[212:215], v[98:101]
	v_mfma_f32_16x16x32_bf16 v[86:89], v[158:161], v[226:229], v[86:89]
	v_mfma_f32_16x16x32_bf16 v[82:85], v[166:169], v[226:229], v[82:85]
	v_mfma_f32_16x16x32_bf16 v[134:137], v[162:165], v[200:203], v[134:137]
	v_mfma_f32_16x16x32_bf16 v[130:133], v[170:173], v[200:203], v[130:133]
	v_mfma_f32_16x16x32_bf16 v[118:121], v[162:165], v[208:211], v[118:121]
	v_mfma_f32_16x16x32_bf16 v[114:117], v[170:173], v[208:211], v[114:117]
	v_mfma_f32_16x16x32_bf16 v[102:105], v[162:165], v[216:219], v[102:105]
	v_mfma_f32_16x16x32_bf16 v[98:101], v[170:173], v[216:219], v[98:101]
	v_mfma_f32_16x16x32_bf16 v[86:89], v[162:165], v[232:235], v[86:89]
	s_barrier
	v_mfma_f32_16x16x32_bf16 v[82:85], v[170:173], v[232:235], v[82:85]
	s_setprio 0
	s_mov_b32 m0, s43
	v_lshl_add_u64 v[174:175], s[86:87], 0, v[148:149]
	s_add_u32 s58, s86, 0x40000
	ds_read_b128 v[182:185], v177 offset:16384
	ds_read_b128 v[200:203], v177 offset:17408
	ds_read_b128 v[204:207], v177 offset:18432
	ds_read_b128 v[208:211], v177 offset:19456
	ds_read_b128 v[212:215], v177 offset:20480
	ds_read_b128 v[216:219], v177 offset:21504
	ds_read_b128 v[226:229], v177 offset:22528
	ds_read_b128 v[232:235], v177 offset:23552
	global_load_lds_dwordx4 v[174:175], off
	v_lshl_add_u64 v[178:179], s[86:87], 0, v[152:153]
	s_mov_b32 m0, s92
	s_addc_u32 s59, s87, 0
	global_load_lds_dwordx4 v[178:179], off
	v_lshl_add_u64 v[180:181], s[58:59], 0, v[148:149]
	s_mov_b32 m0, s93
	v_lshl_add_u64 v[236:237], s[88:89], 0, v[150:151]
	global_load_lds_dwordx4 v[180:181], off
	v_lshl_add_u64 v[180:181], s[58:59], 0, v[152:153]
	s_mov_b32 m0, s94
	s_nop 0
	global_load_lds_dwordx4 v[180:181], off
	v_lshl_add_u64 v[180:181], s[88:89], 0, v[146:147]
	s_mov_b32 m0, s70
	s_nop 0
	global_load_lds_dwordx4 v[180:181], off
	s_mov_b32 m0, s95
	s_nop 0
	global_load_lds_dwordx4 v[236:237], off
	s_waitcnt vmcnt(8)
	s_waitcnt lgkmcnt(0)
	s_barrier
; #define PG8_STAGE(bufoff, gbase, voff) do { _Pragma("unroll") for (int _i = 0; _i < 2; ++_i) \
;         __builtin_amdgcn_global_load_lds((const unsigned*)((const char*)(gbase) + (voff)[_i]), (PG8_LAS unsigned*)(lds + (bufoff) + ldsw + _i * 8192), 16, 0, 0); } while (0)
; #define PG8_LDA(dst, b, h) do { _Pragma("unroll") for (int m = 0; m < 4; ++m) _Pragma("unroll") for (int k = 0; k < 2; ++k) dst[m][k] = *(const PG8_LAS bf16x8*)(lds + PG8_SA(b, h) + aoff + m * 2048 + k * 1024); } while (0)
; #define PG8_LDB(dst, b, h) do { _Pragma("unroll") for (int n = 0; n < 2; ++n) _Pragma("unroll") for (int k = 0; k < 2; ++k) dst[n][k] = *(const PG8_LAS bf16x8*)(lds + PG8_SB(b, h) + boff + n * 2048 + k * 1024); } while (0)
; #define PG8_MMA(ai, bj, At, Bt) do { __builtin_amdgcn_s_setprio(1); _Pragma("unroll") for (int m = 0; m < 4; ++m) _Pragma("unroll") for (int n = 0; n < 2; ++n) _Pragma("unroll") for (int k = 0; k < 2; ++k) \
;         acc[ai][bj][m][n] = __builtin_amdgcn_mfma_f32_16x16x32_bf16(Bt[n][k], At[m][k], acc[ai][bj][m][n], 0, 0, 0); __builtin_amdgcn_s_setprio(0); } while (0)
; #define PG8_WAIT_V(n) asm volatile("s_waitcnt vmcnt(" #n ")" ::: "memory")
; #define PG8_WAIT_L(n) asm volatile("s_waitcnt lgkmcnt(" #n ")" ::: "memory")
; #define PG8_BAR __builtin_amdgcn_s_barrier()
; #define PG8_SCHED __builtin_amdgcn_sched_barrier(0)
; template <class Epi, class Sched, bool ALIGN_EPI = false, bool SP2 = false>
; __device__ __forceinline__ void gemm_phase(PG8_LAS unsigned char* lds, const Gemm g, const Sched& S, const Epi& E, int tid_in) {
;     ...
;             PG8_WAIT_V(8); PG8_WAIT_L(0); PG8_BAR; PG8_MMA(1, 0, At, B0); PG8_MMA(1, 1, At, B1); PG8_BAR; PG8_SCHED;
;             PG8_LDB(B0, 1, 0); PG8_LDB(B1, 1, 1); PG8_SCHED; PG8_LDA(At, 1, 0); PG8_STAGE(PG8_SA(0, 1), a2 + hstep, voffA);
;             PG8_WAIT_V(8); PG8_WAIT_L(0); PG8_BAR; PG8_MMA(0, 0, At, B0); PG8_MMA(0, 1, At, B1); PG8_BAR; PG8_SCHED;
	s_setprio 1
	s_waitcnt lgkmcnt(0)
	v_mfma_f32_16x16x32_bf16 v[76:79], v[32:35], v[182:185], v[76:79]
	v_mfma_f32_16x16x32_bf16 v[72:75], v[44:47], v[182:185], v[72:75]
	v_mfma_f32_16x16x32_bf16 v[60:63], v[32:35], v[204:207], v[60:63]
	v_mfma_f32_16x16x32_bf16 v[56:59], v[44:47], v[204:207], v[56:59]
	v_mfma_f32_16x16x32_bf16 v[28:31], v[32:35], v[212:215], v[28:31]
	v_mfma_f32_16x16x32_bf16 v[24:27], v[44:47], v[212:215], v[24:27]
	v_mfma_f32_16x16x32_bf16 v[12:15], v[32:35], v[226:229], v[12:15]
	v_mfma_f32_16x16x32_bf16 v[8:11], v[44:47], v[226:229], v[8:11]
	v_mfma_f32_16x16x32_bf16 v[76:79], v[36:39], v[200:203], v[76:79]
	v_mfma_f32_16x16x32_bf16 v[72:75], v[48:51], v[200:203], v[72:75]
	v_mfma_f32_16x16x32_bf16 v[60:63], v[36:39], v[208:211], v[60:63]
	v_mfma_f32_16x16x32_bf16 v[56:59], v[48:51], v[208:211], v[56:59]
	v_mfma_f32_16x16x32_bf16 v[28:31], v[36:39], v[216:219], v[28:31]
	v_mfma_f32_16x16x32_bf16 v[24:27], v[48:51], v[216:219], v[24:27]
	v_mfma_f32_16x16x32_bf16 v[12:15], v[36:39], v[232:235], v[12:15]
	v_mfma_f32_16x16x32_bf16 v[8:11], v[48:51], v[232:235], v[8:11]
	s_setprio 0
	s_setprio 1
	v_mfma_f32_16x16x32_bf16 v[40:43], v[166:169], v[204:207], v[40:43]
	v_mfma_f32_16x16x32_bf16 v[20:23], v[158:161], v[212:215], v[20:23]
	v_mfma_f32_16x16x32_bf16 v[16:19], v[166:169], v[212:215], v[16:19]
	v_mfma_f32_16x16x32_bf16 v[4:7], v[158:161], v[226:229], v[4:7]
	v_mfma_f32_16x16x32_bf16 v[0:3], v[166:169], v[226:229], v[0:3]
	v_mfma_f32_16x16x32_bf16 v[32:35], v[158:161], v[182:185], v[68:71]
	v_mfma_f32_16x16x32_bf16 v[36:39], v[166:169], v[182:185], v[64:67]
	v_mfma_f32_16x16x32_bf16 v[44:47], v[158:161], v[204:207], v[52:55]
	v_mfma_f32_16x16x32_bf16 v[40:43], v[170:173], v[208:211], v[40:43]
	v_mfma_f32_16x16x32_bf16 v[20:23], v[162:165], v[216:219], v[20:23]
	v_mfma_f32_16x16x32_bf16 v[16:19], v[170:173], v[216:219], v[16:19]
	v_mfma_f32_16x16x32_bf16 v[4:7], v[162:165], v[232:235], v[4:7]
	v_mfma_f32_16x16x32_bf16 v[0:3], v[170:173], v[232:235], v[0:3]
	v_mfma_f32_16x16x32_bf16 v[32:35], v[162:165], v[200:203], v[32:35]
	v_mfma_f32_16x16x32_bf16 v[36:39], v[170:173], v[200:203], v[36:39]
	s_barrier
	v_mfma_f32_16x16x32_bf16 v[44:47], v[162:165], v[208:211], v[44:47]
	s_setprio 0
	v_or_b32_e32 v48, 0x18000, v194
	v_add_u32_e32 v52, 0x18400, v194
	v_add_u32_e32 v64, 0x18800, v194
	v_add_u32_e32 v68, 0x18c00, v194
	v_or_b32_e32 v81, 0x1c000, v194
	v_add_u32_e32 v162, 0x1c400, v194
	ds_read_b128 v[48:51], v48
	ds_read_b128 v[52:55], v52
	ds_read_b128 v[64:67], v64
	ds_read_b128 v[68:71], v68
	ds_read_b128 v[158:161], v81
	ds_read_b128 v[162:165], v162
	v_add_u32_e32 v81, 0x1c800, v194
	v_add_u32_e32 v170, 0x1cc00, v194
	ds_read_b128 v[166:169], v81
	ds_read_b128 v[170:173], v170
	s_add_u32 s58, s88, 0x40000
	s_addc_u32 s59, s89, 0
	s_mov_b32 m0, s57
	v_lshl_add_u64 v[238:239], s[58:59], 0, v[146:147]
	ds_read_b128 v[182:185], v177 offset:32768
	ds_read_b128 v[200:203], v177 offset:33792
	ds_read_b128 v[204:207], v177 offset:34816
	ds_read_b128 v[208:211], v177 offset:35840
	ds_read_b128 v[212:215], v177 offset:36864
	ds_read_b128 v[216:219], v177 offset:37888
	ds_read_b128 v[226:229], v177 offset:38912
	ds_read_b128 v[232:235], v177 offset:39936
	global_load_lds_dwordx4 v[238:239], off
	v_lshl_add_u64 v[238:239], s[58:59], 0, v[150:151]
	s_mov_b32 m0, s52
	s_nop 0
	global_load_lds_dwordx4 v[238:239], off
	s_waitcnt vmcnt(8)
	s_waitcnt lgkmcnt(0)
	s_barrier
	s_setprio 1
	s_waitcnt lgkmcnt(0)
	v_mfma_f32_16x16x32_bf16 v[142:145], v[48:51], v[182:185], v[142:145]
	v_mfma_f32_16x16x32_bf16 v[138:141], v[64:67], v[182:185], v[138:141]
	v_mfma_f32_16x16x32_bf16 v[126:129], v[48:51], v[204:207], v[126:129]
	v_mfma_f32_16x16x32_bf16 v[122:125], v[64:67], v[204:207], v[122:125]
	v_mfma_f32_16x16x32_bf16 v[110:113], v[48:51], v[212:215], v[110:113]
	v_mfma_f32_16x16x32_bf16 v[106:109], v[64:67], v[212:215], v[106:109]
	v_mfma_f32_16x16x32_bf16 v[94:97], v[48:51], v[226:229], v[94:97]
	v_mfma_f32_16x16x32_bf16 v[90:93], v[64:67], v[226:229], v[90:93]
	v_mfma_f32_16x16x32_bf16 v[142:145], v[52:55], v[200:203], v[142:145]
	v_mfma_f32_16x16x32_bf16 v[138:141], v[68:71], v[200:203], v[138:141]
	v_mfma_f32_16x16x32_bf16 v[126:129], v[52:55], v[208:211], v[126:129]
	v_mfma_f32_16x16x32_bf16 v[122:125], v[68:71], v[208:211], v[122:125]
	v_mfma_f32_16x16x32_bf16 v[110:113], v[52:55], v[216:219], v[110:113]
	v_mfma_f32_16x16x32_bf16 v[106:109], v[68:71], v[216:219], v[106:109]
	v_mfma_f32_16x16x32_bf16 v[94:97], v[52:55], v[232:235], v[94:97]
	v_mfma_f32_16x16x32_bf16 v[90:93], v[68:71], v[232:235], v[90:93]
	s_setprio 0
	s_setprio 1
	v_mfma_f32_16x16x32_bf16 v[134:137], v[158:161], v[182:185], v[134:137]
	v_mfma_f32_16x16x32_bf16 v[130:133], v[166:169], v[182:185], v[130:133]
	v_mfma_f32_16x16x32_bf16 v[118:121], v[158:161], v[204:207], v[118:121]
	v_mfma_f32_16x16x32_bf16 v[114:117], v[166:169], v[204:207], v[114:117]
	v_mfma_f32_16x16x32_bf16 v[102:105], v[158:161], v[212:215], v[102:105]
	v_mfma_f32_16x16x32_bf16 v[98:101], v[166:169], v[212:215], v[98:101]
	v_mfma_f32_16x16x32_bf16 v[86:89], v[158:161], v[226:229], v[86:89]
	v_mfma_f32_16x16x32_bf16 v[82:85], v[166:169], v[226:229], v[82:85]
	v_mfma_f32_16x16x32_bf16 v[134:137], v[162:165], v[200:203], v[134:137]
	v_mfma_f32_16x16x32_bf16 v[130:133], v[170:173], v[200:203], v[130:133]
	v_mfma_f32_16x16x32_bf16 v[118:121], v[162:165], v[208:211], v[118:121]
	v_mfma_f32_16x16x32_bf16 v[114:117], v[170:173], v[208:211], v[114:117]
	v_mfma_f32_16x16x32_bf16 v[102:105], v[162:165], v[216:219], v[102:105]
	v_mfma_f32_16x16x32_bf16 v[98:101], v[170:173], v[216:219], v[98:101]
	v_mfma_f32_16x16x32_bf16 v[86:89], v[162:165], v[232:235], v[86:89]
	s_barrier
; #define PG8_STAGE(bufoff, gbase, voff) do { _Pragma("unroll") for (int _i = 0; _i < 2; ++_i) \
;         __builtin_amdgcn_global_load_lds((const unsigned*)((const char*)(gbase) + (voff)[_i]), (PG8_LAS unsigned*)(lds + (bufoff) + ldsw + _i * 8192), 16, 0, 0); } while (0)
; #define PG8_LDA(dst, b, h) do { _Pragma("unroll") for (int m = 0; m < 4; ++m) _Pragma("unroll") for (int k = 0; k < 2; ++k) dst[m][k] = *(const PG8_LAS bf16x8*)(lds + PG8_SA(b, h) + aoff + m * 2048 + k * 1024); } while (0)
; #define PG8_MMA(ai, bj, At, Bt) do { __builtin_amdgcn_s_setprio(1); _Pragma("unroll") for (int m = 0; m < 4; ++m) _Pragma("unroll") for (int n = 0; n < 2; ++n) _Pragma("unroll") for (int k = 0; k < 2; ++k) \
;         acc[ai][bj][m][n] = __builtin_amdgcn_mfma_f32_16x16x32_bf16(Bt[n][k], At[m][k], acc[ai][bj][m][n], 0, 0, 0); __builtin_amdgcn_s_setprio(0); } while (0)
; #define PG8_WAIT_V(n) asm volatile("s_waitcnt vmcnt(" #n ")" ::: "memory")
; #define PG8_WAIT_L(n) asm volatile("s_waitcnt lgkmcnt(" #n ")" ::: "memory")
; #define PG8_BAR __builtin_amdgcn_s_barrier()
; #define PG8_SCHED __builtin_amdgcn_sched_barrier(0)
; template <class Epi, class Sched, bool ALIGN_EPI = false, bool SP2 = false>
; __device__ __forceinline__ void gemm_phase(PG8_LAS unsigned char* lds, const Gemm g, const Sched& S, const Epi& E, int tid_in) {
;     ...
;             PG8_LDA(At, 1, 1); PG8_STAGE(PG8_SB(1, 0), b3, voffB); PG8_STAGE(PG8_SB(1, 1), b3 + hstep, voffB); PG8_STAGE(PG8_SA(1, 0), a3, voffA);
;             PG8_WAIT_V(8); PG8_WAIT_L(0); PG8_BAR; PG8_MMA(1, 0, At, B0); PG8_MMA(1, 1, At, B1); PG8_BAR; PG8_SCHED;
;     ...
;         if constexpr (ALIGN_EPI) { if (wr == 0) PG8_BAR; }
	v_mfma_f32_16x16x32_bf16 v[82:85], v[170:173], v[232:235], v[82:85]
	s_setprio 0
	s_mov_b32 m0, s67
	v_lshl_add_u64 v[174:175], v[174:175], 0, s[48:49]
	s_add_u32 s58, s86, 0x40080
	ds_read_b128 v[182:185], v177 offset:49152
	ds_read_b128 v[200:203], v177 offset:50176
	ds_read_b128 v[204:207], v177 offset:51200
	ds_read_b128 v[208:211], v177 offset:52224
	ds_read_b128 v[212:215], v177 offset:53248
	ds_read_b128 v[216:219], v177 offset:54272
	ds_read_b128 v[226:229], v177 offset:55296
	ds_read_b128 v[232:235], v177 offset:56320
	global_load_lds_dwordx4 v[174:175], off
	v_lshl_add_u64 v[174:175], v[178:179], 0, s[48:49]
	s_mov_b32 m0, s91
	s_addc_u32 s59, s87, 0
	global_load_lds_dwordx4 v[174:175], off
	v_lshl_add_u64 v[174:175], s[58:59], 0, v[148:149]
	s_mov_b32 m0, s75
	s_nop 0
	global_load_lds_dwordx4 v[174:175], off
	v_lshl_add_u64 v[174:175], s[58:59], 0, v[152:153]
	s_mov_b32 m0, s74
	s_nop 0
	global_load_lds_dwordx4 v[174:175], off
	v_lshl_add_u64 v[174:175], v[180:181], 0, s[48:49]
	s_mov_b32 m0, s53
	s_nop 0
	global_load_lds_dwordx4 v[174:175], off
	v_lshl_add_u64 v[174:175], v[236:237], 0, s[48:49]
	s_mov_b32 m0, s66
	s_nop 0
	global_load_lds_dwordx4 v[174:175], off
	s_waitcnt vmcnt(8)
	s_waitcnt lgkmcnt(0)
	s_barrier
	s_setprio 1
	s_waitcnt lgkmcnt(0)
	v_mfma_f32_16x16x32_bf16 v[76:79], v[48:51], v[182:185], v[76:79]
	v_mfma_f32_16x16x32_bf16 v[72:75], v[64:67], v[182:185], v[72:75]
	v_mfma_f32_16x16x32_bf16 v[60:63], v[48:51], v[204:207], v[60:63]
	v_mfma_f32_16x16x32_bf16 v[56:59], v[64:67], v[204:207], v[56:59]
	v_mfma_f32_16x16x32_bf16 v[28:31], v[48:51], v[212:215], v[28:31]
	v_mfma_f32_16x16x32_bf16 v[24:27], v[64:67], v[212:215], v[24:27]
	v_mfma_f32_16x16x32_bf16 v[12:15], v[48:51], v[226:229], v[12:15]
	v_mfma_f32_16x16x32_bf16 v[8:11], v[64:67], v[226:229], v[8:11]
	v_mfma_f32_16x16x32_bf16 v[76:79], v[52:55], v[200:203], v[76:79]
	v_mfma_f32_16x16x32_bf16 v[72:75], v[68:71], v[200:203], v[72:75]
	v_mfma_f32_16x16x32_bf16 v[60:63], v[52:55], v[208:211], v[60:63]
	v_mfma_f32_16x16x32_bf16 v[56:59], v[68:71], v[208:211], v[56:59]
	v_mfma_f32_16x16x32_bf16 v[28:31], v[52:55], v[216:219], v[28:31]
	v_mfma_f32_16x16x32_bf16 v[24:27], v[68:71], v[216:219], v[24:27]
	v_mfma_f32_16x16x32_bf16 v[12:15], v[52:55], v[232:235], v[12:15]
	v_mfma_f32_16x16x32_bf16 v[8:11], v[68:71], v[232:235], v[8:11]
	s_setprio 0
	s_setprio 1
	v_mfma_f32_16x16x32_bf16 v[32:35], v[158:161], v[182:185], v[32:35]
	v_mfma_f32_16x16x32_bf16 v[68:71], v[162:165], v[200:203], v[32:35]
	v_mfma_f32_16x16x32_bf16 v[32:35], v[166:169], v[182:185], v[36:39]
	v_mfma_f32_16x16x32_bf16 v[64:67], v[170:173], v[200:203], v[32:35]
	v_mfma_f32_16x16x32_bf16 v[32:35], v[158:161], v[204:207], v[44:47]
	v_mfma_f32_16x16x32_bf16 v[52:55], v[162:165], v[208:211], v[32:35]
	v_mfma_f32_16x16x32_bf16 v[32:35], v[166:169], v[204:207], v[40:43]
	v_mfma_f32_16x16x32_bf16 v[20:23], v[158:161], v[212:215], v[20:23]
	v_mfma_f32_16x16x32_bf16 v[16:19], v[166:169], v[212:215], v[16:19]
	v_mfma_f32_16x16x32_bf16 v[4:7], v[158:161], v[226:229], v[4:7]
	v_mfma_f32_16x16x32_bf16 v[0:3], v[166:169], v[226:229], v[0:3]
	v_mfma_f32_16x16x32_bf16 v[40:43], v[170:173], v[208:211], v[32:35]
	v_mfma_f32_16x16x32_bf16 v[20:23], v[162:165], v[216:219], v[20:23]
	v_mfma_f32_16x16x32_bf16 v[16:19], v[170:173], v[216:219], v[16:19]
	v_mfma_f32_16x16x32_bf16 v[4:7], v[162:165], v[232:235], v[4:7]
	s_barrier
	v_mfma_f32_16x16x32_bf16 v[0:3], v[170:173], v[232:235], v[0:3]
	s_setprio 0
	s_add_i32 s27, s27, 2
	s_add_u32 s84, s84, 0x100
	s_addc_u32 s85, s85, 0
	s_add_u32 s25, s25, 0x100
	s_addc_u32 s26, s26, 0
	s_cmp_gt_u32 s27, 13
	s_cbranch_scc0 .LBB0_158
	v_readlane_b32 s22, v254, 30
	v_readlane_b32 s23, v254, 31
	s_and_b64 vcc, exec, s[22:23]
	s_cbranch_vccz .Ltrail_161
	s_barrier
	s_branch .LBB0_161
.Ltrail_161:
	s_setprio 1

; #define PG8_STAGE(bufoff, gbase, voff) do { _Pragma("unroll") for (int _i = 0; _i < 2; ++_i) \
;         __builtin_amdgcn_global_load_lds((const unsigned*)((const char*)(gbase) + (voff)[_i]), (PG8_LAS unsigned*)(lds + (bufoff) + ldsw + _i * 8192), 16, 0, 0); } while (0)
; #define PG8_LDA(dst, b, h) do { _Pragma("unroll") for (int m = 0; m < 4; ++m) _Pragma("unroll") for (int k = 0; k < 2; ++k) dst[m][k] = *(const PG8_LAS bf16x8*)(lds + PG8_SA(b, h) + aoff + m * 2048 + k * 1024); } while (0)
; #define PG8_LDB(dst, b, h) do { _Pragma("unroll") for (int n = 0; n < 2; ++n) _Pragma("unroll") for (int k = 0; k < 2; ++k) dst[n][k] = *(const PG8_LAS bf16x8*)(lds + PG8_SB(b, h) + boff + n * 2048 + k * 1024); } while (0)
; #define PG8_MMA(ai, bj, At, Bt) do { __builtin_amdgcn_s_setprio(1); _Pragma("unroll") for (int m = 0; m < 4; ++m) _Pragma("unroll") for (int n = 0; n < 2; ++n) _Pragma("unroll") for (int k = 0; k < 2; ++k) \
;         acc[ai][bj][m][n] = __builtin_amdgcn_mfma_f32_16x16x32_bf16(Bt[n][k], At[m][k], acc[ai][bj][m][n], 0, 0, 0); __builtin_amdgcn_s_setprio(0); } while (0)
; #define PG8_WAIT_V(n) asm volatile("s_waitcnt vmcnt(" #n ")" ::: "memory")
; #define PG8_WAIT_L(n) asm volatile("s_waitcnt lgkmcnt(" #n ")" ::: "memory")
; #define PG8_BAR __builtin_amdgcn_s_barrier()
; #define PG8_SCHED __builtin_amdgcn_sched_barrier(0)
; template <class Epi, class Sched, bool ALIGN_EPI = false, bool SP2 = false>
; __device__ __forceinline__ void gemm_phase(PG8_LAS unsigned char* lds, const Gemm g, const Sched& S, const Epi& E, int tid_in) {
;     ...
;             PG8_LDB(B0, 0, 0); PG8_LDB(B1, 0, 1); PG8_SCHED; PG8_LDA(At, 0, 0); PG8_STAGE(PG8_SA(1, 1), a1 + hstep, voffA);
;             PG8_WAIT_V(8); PG8_WAIT_L(0); PG8_BAR; PG8_MMA(0, 0, At, B0); PG8_MMA(0, 1, At, B1); PG8_BAR; PG8_SCHED;
;             PG8_LDA(At, 0, 1); PG8_STAGE(PG8_SB(0, 0), b2, voffB); PG8_STAGE(PG8_SB(0, 1), b2 + hstep, voffB); PG8_STAGE(PG8_SA(0, 0), a2, voffA);
;             PG8_WAIT_V(8); PG8_WAIT_L(0); PG8_BAR; PG8_MMA(1, 0, At, B0); PG8_MMA(1, 1, At, B1); PG8_BAR; PG8_SCHED;
.LBB0_440:
	v_or_b32_e32 v130, 0x10000, v248
	v_add_u32_e32 v134, 0x10400, v248
	v_add_u32_e32 v138, 0x10800, v248
	v_add_u32_e32 v142, 0x10c00, v248
	v_or_b32_e32 v146, 0x14000, v248
	v_add_u32_e32 v150, 0x14400, v248
	v_add_u32_e32 v154, 0x14800, v248
	v_add_u32_e32 v158, 0x14c00, v248
	ds_read_b128 v[130:133], v130
	ds_read_b128 v[134:137], v134
	ds_read_b128 v[138:141], v138
	ds_read_b128 v[142:145], v142
	ds_read_b128 v[146:149], v146
	ds_read_b128 v[150:153], v150
	ds_read_b128 v[154:157], v154
	ds_read_b128 v[158:161], v158
	s_add_u32 s80, s78, 0xfffc0080
	s_addc_u32 s81, s79, -1
	s_cmp_eq_u32 s87, 12
	s_cselect_b32 s83, s71, s81
	s_cselect_b32 s82, s77, s80
	s_cselect_b32 s81, s67, s86
	s_cselect_b32 s80, s84, s85
	v_lshl_add_u64 v[178:179], s[78:79], 0, v[202:203]
	s_add_i32 m0, s57, 0xc000
	ds_read_b128 v[162:165], v247
	ds_read_b128 v[166:169], v247 offset:1024
	ds_read_b128 v[170:173], v247 offset:2048
	ds_read_b128 v[174:177], v247 offset:3072
	ds_read_b128 v[182:185], v247 offset:4096
	ds_read_b128 v[212:215], v247 offset:5120
	ds_read_b128 v[226:229], v247 offset:6144
	ds_read_b128 v[232:235], v247 offset:7168
	global_load_lds_dwordx4 v[178:179], off
	v_lshl_add_u64 v[178:179], s[78:79], 0, v[204:205]
	s_add_i32 m0, s57, 0xe000
	s_nop 0
	global_load_lds_dwordx4 v[178:179], off
	s_waitcnt vmcnt(8)
	s_waitcnt lgkmcnt(0)
	s_barrier
	s_setprio 1
	s_waitcnt lgkmcnt(0)
	v_mfma_f32_16x16x32_bf16 v[126:129], v[130:133], v[162:165], v[126:129]
	v_mfma_f32_16x16x32_bf16 v[122:125], v[138:141], v[162:165], v[122:125]
	v_mfma_f32_16x16x32_bf16 v[114:117], v[130:133], v[170:173], v[114:117]
	v_mfma_f32_16x16x32_bf16 v[106:109], v[138:141], v[170:173], v[106:109]
	v_mfma_f32_16x16x32_bf16 v[98:101], v[130:133], v[182:185], v[98:101]
	v_mfma_f32_16x16x32_bf16 v[90:93], v[138:141], v[182:185], v[90:93]
	v_mfma_f32_16x16x32_bf16 v[76:79], v[130:133], v[226:229], v[76:79]
	v_mfma_f32_16x16x32_bf16 v[72:75], v[138:141], v[226:229], v[72:75]
	v_mfma_f32_16x16x32_bf16 v[126:129], v[134:137], v[166:169], v[126:129]
	v_mfma_f32_16x16x32_bf16 v[122:125], v[142:145], v[166:169], v[122:125]
	v_mfma_f32_16x16x32_bf16 v[114:117], v[134:137], v[174:177], v[114:117]
	v_mfma_f32_16x16x32_bf16 v[106:109], v[142:145], v[174:177], v[106:109]
	v_mfma_f32_16x16x32_bf16 v[98:101], v[134:137], v[212:215], v[98:101]
	v_mfma_f32_16x16x32_bf16 v[90:93], v[142:145], v[212:215], v[90:93]
	v_mfma_f32_16x16x32_bf16 v[76:79], v[134:137], v[232:235], v[76:79]
	v_mfma_f32_16x16x32_bf16 v[72:75], v[142:145], v[232:235], v[72:75]
	s_setprio 0
	s_setprio 1
	v_mfma_f32_16x16x32_bf16 v[118:121], v[146:149], v[162:165], v[118:121]
	v_mfma_f32_16x16x32_bf16 v[110:113], v[154:157], v[162:165], v[110:113]
	v_mfma_f32_16x16x32_bf16 v[102:105], v[146:149], v[170:173], v[102:105]
	v_mfma_f32_16x16x32_bf16 v[94:97], v[154:157], v[170:173], v[94:97]
	v_mfma_f32_16x16x32_bf16 v[86:89], v[146:149], v[182:185], v[86:89]
	v_mfma_f32_16x16x32_bf16 v[82:85], v[154:157], v[182:185], v[82:85]
	v_mfma_f32_16x16x32_bf16 v[68:71], v[146:149], v[226:229], v[68:71]
	v_mfma_f32_16x16x32_bf16 v[64:67], v[154:157], v[226:229], v[64:67]
	v_mfma_f32_16x16x32_bf16 v[118:121], v[150:153], v[166:169], v[118:121]
	v_mfma_f32_16x16x32_bf16 v[110:113], v[158:161], v[166:169], v[110:113]
	v_mfma_f32_16x16x32_bf16 v[102:105], v[150:153], v[174:177], v[102:105]
	v_mfma_f32_16x16x32_bf16 v[94:97], v[158:161], v[174:177], v[94:97]
	v_mfma_f32_16x16x32_bf16 v[86:89], v[150:153], v[212:215], v[86:89]
	v_mfma_f32_16x16x32_bf16 v[82:85], v[158:161], v[212:215], v[82:85]
	v_mfma_f32_16x16x32_bf16 v[68:71], v[150:153], v[232:235], v[68:71]
	s_barrier
	v_mfma_f32_16x16x32_bf16 v[64:67], v[158:161], v[232:235], v[64:67]
	s_setprio 0
	s_mov_b32 m0, s20
	v_lshl_add_u64 v[178:179], s[80:81], 0, v[198:199]
	s_add_u32 s88, s80, 0x40000
	ds_read_b128 v[162:165], v247 offset:16384
	ds_read_b128 v[166:169], v247 offset:17408
	ds_read_b128 v[170:173], v247 offset:18432
	ds_read_b128 v[174:177], v247 offset:19456
	ds_read_b128 v[182:185], v247 offset:20480
	ds_read_b128 v[212:215], v247 offset:21504
	ds_read_b128 v[226:229], v247 offset:22528
	ds_read_b128 v[232:235], v247 offset:23552
	global_load_lds_dwordx4 v[178:179], off
	v_lshl_add_u64 v[180:181], s[80:81], 0, v[194:195]
	s_mov_b32 m0, s21
	s_addc_u32 s89, s81, 0
	global_load_lds_dwordx4 v[180:181], off
	v_lshl_add_u64 v[208:209], s[88:89], 0, v[198:199]
	s_mov_b32 m0, s22
	v_lshl_add_u64 v[218:219], s[82:83], 0, v[196:197]
	global_load_lds_dwordx4 v[208:209], off
	v_lshl_add_u64 v[208:209], s[88:89], 0, v[194:195]
	s_mov_b32 m0, s23
	s_nop 0
	global_load_lds_dwordx4 v[208:209], off
	v_lshl_add_u64 v[208:209], s[82:83], 0, v[200:201]
	s_mov_b32 m0, s57
	s_nop 0
	global_load_lds_dwordx4 v[208:209], off
	s_mov_b32 m0, s24
	s_nop 0
	global_load_lds_dwordx4 v[218:219], off
	s_waitcnt vmcnt(8)
	s_waitcnt lgkmcnt(0)
	s_barrier
; #define PG8_STAGE(bufoff, gbase, voff) do { _Pragma("unroll") for (int _i = 0; _i < 2; ++_i) \
;         __builtin_amdgcn_global_load_lds((const unsigned*)((const char*)(gbase) + (voff)[_i]), (PG8_LAS unsigned*)(lds + (bufoff) + ldsw + _i * 8192), 16, 0, 0); } while (0)
; #define PG8_LDA(dst, b, h) do { _Pragma("unroll") for (int m = 0; m < 4; ++m) _Pragma("unroll") for (int k = 0; k < 2; ++k) dst[m][k] = *(const PG8_LAS bf16x8*)(lds + PG8_SA(b, h) + aoff + m * 2048 + k * 1024); } while (0)
; #define PG8_LDB(dst, b, h) do { _Pragma("unroll") for (int n = 0; n < 2; ++n) _Pragma("unroll") for (int k = 0; k < 2; ++k) dst[n][k] = *(const PG8_LAS bf16x8*)(lds + PG8_SB(b, h) + boff + n * 2048 + k * 1024); } while (0)
; #define PG8_MMA(ai, bj, At, Bt) do { __builtin_amdgcn_s_setprio(1); _Pragma("unroll") for (int m = 0; m < 4; ++m) _Pragma("unroll") for (int n = 0; n < 2; ++n) _Pragma("unroll") for (int k = 0; k < 2; ++k) \
;         acc[ai][bj][m][n] = __builtin_amdgcn_mfma_f32_16x16x32_bf16(Bt[n][k], At[m][k], acc[ai][bj][m][n], 0, 0, 0); __builtin_amdgcn_s_setprio(0); } while (0)
; #define PG8_WAIT_V(n) asm volatile("s_waitcnt vmcnt(" #n ")" ::: "memory")
; #define PG8_WAIT_L(n) asm volatile("s_waitcnt lgkmcnt(" #n ")" ::: "memory")
; #define PG8_BAR __builtin_amdgcn_s_barrier()
; #define PG8_SCHED __builtin_amdgcn_sched_barrier(0)
; template <class Epi, class Sched, bool ALIGN_EPI = false, bool SP2 = false>
; __device__ __forceinline__ void gemm_phase(PG8_LAS unsigned char* lds, const Gemm g, const Sched& S, const Epi& E, int tid_in) {
;     ...
;             PG8_WAIT_V(8); PG8_WAIT_L(0); PG8_BAR; PG8_MMA(1, 0, At, B0); PG8_MMA(1, 1, At, B1); PG8_BAR; PG8_SCHED;
;             PG8_LDB(B0, 1, 0); PG8_LDB(B1, 1, 1); PG8_SCHED; PG8_LDA(At, 1, 0); PG8_STAGE(PG8_SA(0, 1), a2 + hstep, voffA);
;             PG8_WAIT_V(8); PG8_WAIT_L(0); PG8_BAR; PG8_MMA(0, 0, At, B0); PG8_MMA(0, 1, At, B1); PG8_BAR; PG8_SCHED;
	s_setprio 1
	s_waitcnt lgkmcnt(0)
	v_mfma_f32_16x16x32_bf16 v[60:63], v[130:133], v[162:165], v[60:63]
	v_mfma_f32_16x16x32_bf16 v[56:59], v[138:141], v[162:165], v[56:59]
	v_mfma_f32_16x16x32_bf16 v[44:47], v[130:133], v[170:173], v[44:47]
	v_mfma_f32_16x16x32_bf16 v[40:43], v[138:141], v[170:173], v[40:43]
	v_mfma_f32_16x16x32_bf16 v[28:31], v[130:133], v[182:185], v[28:31]
	v_mfma_f32_16x16x32_bf16 v[24:27], v[138:141], v[182:185], v[24:27]
	v_mfma_f32_16x16x32_bf16 v[12:15], v[130:133], v[226:229], v[12:15]
	v_mfma_f32_16x16x32_bf16 v[8:11], v[138:141], v[226:229], v[8:11]
	v_mfma_f32_16x16x32_bf16 v[60:63], v[134:137], v[166:169], v[60:63]
	v_mfma_f32_16x16x32_bf16 v[56:59], v[142:145], v[166:169], v[56:59]
	v_mfma_f32_16x16x32_bf16 v[44:47], v[134:137], v[174:177], v[44:47]
	v_mfma_f32_16x16x32_bf16 v[40:43], v[142:145], v[174:177], v[40:43]
	v_mfma_f32_16x16x32_bf16 v[28:31], v[134:137], v[212:215], v[28:31]
	v_mfma_f32_16x16x32_bf16 v[24:27], v[142:145], v[212:215], v[24:27]
	v_mfma_f32_16x16x32_bf16 v[12:15], v[134:137], v[232:235], v[12:15]
	v_mfma_f32_16x16x32_bf16 v[8:11], v[142:145], v[232:235], v[8:11]
	s_setprio 0
	s_setprio 1
	v_mfma_f32_16x16x32_bf16 v[52:55], v[146:149], v[162:165], v[52:55]
	v_mfma_f32_16x16x32_bf16 v[48:51], v[154:157], v[162:165], v[48:51]
	v_mfma_f32_16x16x32_bf16 v[36:39], v[146:149], v[170:173], v[36:39]
	v_mfma_f32_16x16x32_bf16 v[32:35], v[154:157], v[170:173], v[32:35]
	v_mfma_f32_16x16x32_bf16 v[20:23], v[146:149], v[182:185], v[20:23]
	v_mfma_f32_16x16x32_bf16 v[16:19], v[154:157], v[182:185], v[16:19]
	v_mfma_f32_16x16x32_bf16 v[4:7], v[146:149], v[226:229], v[4:7]
	v_mfma_f32_16x16x32_bf16 v[0:3], v[154:157], v[226:229], v[0:3]
	v_mfma_f32_16x16x32_bf16 v[52:55], v[150:153], v[166:169], v[52:55]
	v_mfma_f32_16x16x32_bf16 v[48:51], v[158:161], v[166:169], v[48:51]
	v_mfma_f32_16x16x32_bf16 v[36:39], v[150:153], v[174:177], v[36:39]
	v_mfma_f32_16x16x32_bf16 v[32:35], v[158:161], v[174:177], v[32:35]
	v_mfma_f32_16x16x32_bf16 v[20:23], v[150:153], v[212:215], v[20:23]
	v_mfma_f32_16x16x32_bf16 v[16:19], v[158:161], v[212:215], v[16:19]
	v_mfma_f32_16x16x32_bf16 v[4:7], v[150:153], v[232:235], v[4:7]
	s_barrier
	v_mfma_f32_16x16x32_bf16 v[0:3], v[158:161], v[232:235], v[0:3]
	s_setprio 0
	v_or_b32_e32 v130, 0x18000, v248
	v_add_u32_e32 v134, 0x18400, v248
	v_add_u32_e32 v138, 0x18800, v248
	v_add_u32_e32 v142, 0x18c00, v248
	v_or_b32_e32 v146, 0x1c000, v248
	v_add_u32_e32 v150, 0x1c400, v248
	v_add_u32_e32 v154, 0x1c800, v248
	v_add_u32_e32 v158, 0x1cc00, v248
	ds_read_b128 v[130:133], v130
	ds_read_b128 v[134:137], v134
	ds_read_b128 v[138:141], v138
	ds_read_b128 v[142:145], v142
	ds_read_b128 v[146:149], v146
	ds_read_b128 v[150:153], v150
	ds_read_b128 v[154:157], v154
	ds_read_b128 v[158:161], v158
	s_add_u32 s82, s82, 0x40000
	s_addc_u32 s83, s83, 0
	s_mov_b32 m0, s25
	v_lshl_add_u64 v[236:237], s[82:83], 0, v[200:201]
	ds_read_b128 v[162:165], v247 offset:32768
	ds_read_b128 v[166:169], v247 offset:33792
	ds_read_b128 v[170:173], v247 offset:34816
	ds_read_b128 v[174:177], v247 offset:35840
	ds_read_b128 v[182:185], v247 offset:36864
	ds_read_b128 v[212:215], v247 offset:37888
	ds_read_b128 v[226:229], v247 offset:38912
	ds_read_b128 v[232:235], v247 offset:39936
	global_load_lds_dwordx4 v[236:237], off
	v_lshl_add_u64 v[236:237], s[82:83], 0, v[196:197]
	s_mov_b32 m0, s26
	s_nop 0
	global_load_lds_dwordx4 v[236:237], off
	s_waitcnt vmcnt(8)
	s_waitcnt lgkmcnt(0)
	s_barrier
	s_setprio 1
	s_waitcnt lgkmcnt(0)
	v_mfma_f32_16x16x32_bf16 v[126:129], v[130:133], v[162:165], v[126:129]
	v_mfma_f32_16x16x32_bf16 v[122:125], v[138:141], v[162:165], v[122:125]
	v_mfma_f32_16x16x32_bf16 v[114:117], v[130:133], v[170:173], v[114:117]
	v_mfma_f32_16x16x32_bf16 v[106:109], v[138:141], v[170:173], v[106:109]
	v_mfma_f32_16x16x32_bf16 v[98:101], v[130:133], v[182:185], v[98:101]
	v_mfma_f32_16x16x32_bf16 v[90:93], v[138:141], v[182:185], v[90:93]
	v_mfma_f32_16x16x32_bf16 v[76:79], v[130:133], v[226:229], v[76:79]
	v_mfma_f32_16x16x32_bf16 v[72:75], v[138:141], v[226:229], v[72:75]
	v_mfma_f32_16x16x32_bf16 v[126:129], v[134:137], v[166:169], v[126:129]
	v_mfma_f32_16x16x32_bf16 v[122:125], v[142:145], v[166:169], v[122:125]
	v_mfma_f32_16x16x32_bf16 v[114:117], v[134:137], v[174:177], v[114:117]
	v_mfma_f32_16x16x32_bf16 v[106:109], v[142:145], v[174:177], v[106:109]
	v_mfma_f32_16x16x32_bf16 v[98:101], v[134:137], v[212:215], v[98:101]
	v_mfma_f32_16x16x32_bf16 v[90:93], v[142:145], v[212:215], v[90:93]
	v_mfma_f32_16x16x32_bf16 v[76:79], v[134:137], v[232:235], v[76:79]
	v_mfma_f32_16x16x32_bf16 v[72:75], v[142:145], v[232:235], v[72:75]
	s_setprio 0
	s_setprio 1
	v_mfma_f32_16x16x32_bf16 v[118:121], v[146:149], v[162:165], v[118:121]
	v_mfma_f32_16x16x32_bf16 v[110:113], v[154:157], v[162:165], v[110:113]
	v_mfma_f32_16x16x32_bf16 v[102:105], v[146:149], v[170:173], v[102:105]
	v_mfma_f32_16x16x32_bf16 v[94:97], v[154:157], v[170:173], v[94:97]
	v_mfma_f32_16x16x32_bf16 v[86:89], v[146:149], v[182:185], v[86:89]
	v_mfma_f32_16x16x32_bf16 v[82:85], v[154:157], v[182:185], v[82:85]
	v_mfma_f32_16x16x32_bf16 v[68:71], v[146:149], v[226:229], v[68:71]
	v_mfma_f32_16x16x32_bf16 v[64:67], v[154:157], v[226:229], v[64:67]
	v_mfma_f32_16x16x32_bf16 v[118:121], v[150:153], v[166:169], v[118:121]
	v_mfma_f32_16x16x32_bf16 v[110:113], v[158:161], v[166:169], v[110:113]
	v_mfma_f32_16x16x32_bf16 v[102:105], v[150:153], v[174:177], v[102:105]
	v_mfma_f32_16x16x32_bf16 v[94:97], v[158:161], v[174:177], v[94:97]
	v_mfma_f32_16x16x32_bf16 v[86:89], v[150:153], v[212:215], v[86:89]
	v_mfma_f32_16x16x32_bf16 v[82:85], v[158:161], v[212:215], v[82:85]
	v_mfma_f32_16x16x32_bf16 v[68:71], v[150:153], v[232:235], v[68:71]
	s_barrier
; #define PG8_STAGE(bufoff, gbase, voff) do { _Pragma("unroll") for (int _i = 0; _i < 2; ++_i) \
;         __builtin_amdgcn_global_load_lds((const unsigned*)((const char*)(gbase) + (voff)[_i]), (PG8_LAS unsigned*)(lds + (bufoff) + ldsw + _i * 8192), 16, 0, 0); } while (0)
; #define PG8_LDA(dst, b, h) do { _Pragma("unroll") for (int m = 0; m < 4; ++m) _Pragma("unroll") for (int k = 0; k < 2; ++k) dst[m][k] = *(const PG8_LAS bf16x8*)(lds + PG8_SA(b, h) + aoff + m * 2048 + k * 1024); } while (0)
; #define PG8_MMA(ai, bj, At, Bt) do { __builtin_amdgcn_s_setprio(1); _Pragma("unroll") for (int m = 0; m < 4; ++m) _Pragma("unroll") for (int n = 0; n < 2; ++n) _Pragma("unroll") for (int k = 0; k < 2; ++k) \
;         acc[ai][bj][m][n] = __builtin_amdgcn_mfma_f32_16x16x32_bf16(Bt[n][k], At[m][k], acc[ai][bj][m][n], 0, 0, 0); __builtin_amdgcn_s_setprio(0); } while (0)
; #define PG8_WAIT_V(n) asm volatile("s_waitcnt vmcnt(" #n ")" ::: "memory")
; #define PG8_WAIT_L(n) asm volatile("s_waitcnt lgkmcnt(" #n ")" ::: "memory")
; #define PG8_BAR __builtin_amdgcn_s_barrier()
; #define PG8_SCHED __builtin_amdgcn_sched_barrier(0)
; template <class Epi, class Sched, bool ALIGN_EPI = false, bool SP2 = false>
; __device__ __forceinline__ void gemm_phase(PG8_LAS unsigned char* lds, const Gemm g, const Sched& S, const Epi& E, int tid_in) {
;     ...
;             PG8_LDA(At, 1, 1); PG8_STAGE(PG8_SB(1, 0), b3, voffB); PG8_STAGE(PG8_SB(1, 1), b3 + hstep, voffB); PG8_STAGE(PG8_SA(1, 0), a3, voffA);
;             PG8_WAIT_V(8); PG8_WAIT_L(0); PG8_BAR; PG8_MMA(1, 0, At, B0); PG8_MMA(1, 1, At, B1); PG8_BAR; PG8_SCHED;
;     ...
;         if constexpr (ALIGN_EPI) { if (wr == 0) PG8_BAR; }
	v_mfma_f32_16x16x32_bf16 v[64:67], v[158:161], v[232:235], v[64:67]
	s_setprio 0
	s_mov_b32 m0, s27
	v_lshl_add_u64 v[178:179], v[178:179], 0, s[48:49]
	s_add_u32 s80, s80, 0x40080
	ds_read_b128 v[162:165], v247 offset:49152
	ds_read_b128 v[166:169], v247 offset:50176
	ds_read_b128 v[170:173], v247 offset:51200
	ds_read_b128 v[174:177], v247 offset:52224
	ds_read_b128 v[182:185], v247 offset:53248
	ds_read_b128 v[212:215], v247 offset:54272
	ds_read_b128 v[226:229], v247 offset:55296
	ds_read_b128 v[232:235], v247 offset:56320
	global_load_lds_dwordx4 v[178:179], off
	v_lshl_add_u64 v[178:179], v[180:181], 0, s[48:49]
	s_mov_b32 m0, s58
	s_addc_u32 s81, s81, 0
	global_load_lds_dwordx4 v[178:179], off
	v_lshl_add_u64 v[178:179], s[80:81], 0, v[198:199]
	s_mov_b32 m0, s63
	s_nop 0
	global_load_lds_dwordx4 v[178:179], off
	v_lshl_add_u64 v[178:179], s[80:81], 0, v[194:195]
	s_mov_b32 m0, s64
	s_nop 0
	global_load_lds_dwordx4 v[178:179], off
	v_lshl_add_u64 v[178:179], v[208:209], 0, s[48:49]
	s_mov_b32 m0, s59
	s_nop 0
	global_load_lds_dwordx4 v[178:179], off
	v_lshl_add_u64 v[178:179], v[218:219], 0, s[48:49]
	s_mov_b32 m0, s62
	s_nop 0
	global_load_lds_dwordx4 v[178:179], off
	s_waitcnt vmcnt(8)
	s_waitcnt lgkmcnt(0)
	s_barrier
	s_setprio 1
	s_waitcnt lgkmcnt(0)
	v_mfma_f32_16x16x32_bf16 v[60:63], v[130:133], v[162:165], v[60:63]
	v_mfma_f32_16x16x32_bf16 v[56:59], v[138:141], v[162:165], v[56:59]
	v_mfma_f32_16x16x32_bf16 v[44:47], v[130:133], v[170:173], v[44:47]
	v_mfma_f32_16x16x32_bf16 v[40:43], v[138:141], v[170:173], v[40:43]
	v_mfma_f32_16x16x32_bf16 v[28:31], v[130:133], v[182:185], v[28:31]
	v_mfma_f32_16x16x32_bf16 v[24:27], v[138:141], v[182:185], v[24:27]
	v_mfma_f32_16x16x32_bf16 v[12:15], v[130:133], v[226:229], v[12:15]
	v_mfma_f32_16x16x32_bf16 v[8:11], v[138:141], v[226:229], v[8:11]
	v_mfma_f32_16x16x32_bf16 v[60:63], v[134:137], v[166:169], v[60:63]
	v_mfma_f32_16x16x32_bf16 v[56:59], v[142:145], v[166:169], v[56:59]
	v_mfma_f32_16x16x32_bf16 v[44:47], v[134:137], v[174:177], v[44:47]
	v_mfma_f32_16x16x32_bf16 v[40:43], v[142:145], v[174:177], v[40:43]
	v_mfma_f32_16x16x32_bf16 v[28:31], v[134:137], v[212:215], v[28:31]
	v_mfma_f32_16x16x32_bf16 v[24:27], v[142:145], v[212:215], v[24:27]
	v_mfma_f32_16x16x32_bf16 v[12:15], v[134:137], v[232:235], v[12:15]
	v_mfma_f32_16x16x32_bf16 v[8:11], v[142:145], v[232:235], v[8:11]
	s_setprio 0
	s_setprio 1
	v_mfma_f32_16x16x32_bf16 v[52:55], v[146:149], v[162:165], v[52:55]
	v_mfma_f32_16x16x32_bf16 v[48:51], v[154:157], v[162:165], v[48:51]
	v_mfma_f32_16x16x32_bf16 v[36:39], v[146:149], v[170:173], v[36:39]
	v_mfma_f32_16x16x32_bf16 v[32:35], v[154:157], v[170:173], v[32:35]
	v_mfma_f32_16x16x32_bf16 v[20:23], v[146:149], v[182:185], v[20:23]
	v_mfma_f32_16x16x32_bf16 v[16:19], v[154:157], v[182:185], v[16:19]
	v_mfma_f32_16x16x32_bf16 v[4:7], v[146:149], v[226:229], v[4:7]
	v_mfma_f32_16x16x32_bf16 v[0:3], v[154:157], v[226:229], v[0:3]
	v_mfma_f32_16x16x32_bf16 v[52:55], v[150:153], v[166:169], v[52:55]
	v_mfma_f32_16x16x32_bf16 v[48:51], v[158:161], v[166:169], v[48:51]
	v_mfma_f32_16x16x32_bf16 v[36:39], v[150:153], v[174:177], v[36:39]
	v_mfma_f32_16x16x32_bf16 v[32:35], v[158:161], v[174:177], v[32:35]
	v_mfma_f32_16x16x32_bf16 v[20:23], v[150:153], v[212:215], v[20:23]
	v_mfma_f32_16x16x32_bf16 v[16:19], v[158:161], v[212:215], v[16:19]
	v_mfma_f32_16x16x32_bf16 v[4:7], v[150:153], v[232:235], v[4:7]
	s_barrier
	v_mfma_f32_16x16x32_bf16 v[0:3], v[158:161], v[232:235], v[0:3]
	s_setprio 0
	s_add_i32 s87, s87, 2
	s_add_u32 s78, s78, 0x100
	s_addc_u32 s79, s79, 0
	s_add_u32 s85, s85, 0x100
	s_addc_u32 s86, s86, 0
	s_cmp_gt_u32 s87, 13
	s_cbranch_scc0 .LBB0_440
	v_mov_b32_e32 v239, 0x60
	v_mov_b32_e32 v236, 0xc0
	s_and_b64 vcc, exec, s[42:43]
	s_cbranch_vccz .Ltrail_443
	s_barrier
	s_branch .LBB0_443

; #define PG8_STAGE(bufoff, gbase, voff) do { _Pragma("unroll") for (int _i = 0; _i < 2; ++_i) \
;         __builtin_amdgcn_global_load_lds((const unsigned*)((const char*)(gbase) + (voff)[_i]), (PG8_LAS unsigned*)(lds + (bufoff) + ldsw + _i * 8192), 16, 0, 0); } while (0)
; #define PG8_LDA(dst, b, h) do { _Pragma("unroll") for (int m = 0; m < 4; ++m) _Pragma("unroll") for (int k = 0; k < 2; ++k) dst[m][k] = *(const PG8_LAS bf16x8*)(lds + PG8_SA(b, h) + aoff + m * 2048 + k * 1024); } while (0)
; #define PG8_LDB(dst, b, h) do { _Pragma("unroll") for (int n = 0; n < 2; ++n) _Pragma("unroll") for (int k = 0; k < 2; ++k) dst[n][k] = *(const PG8_LAS bf16x8*)(lds + PG8_SB(b, h) + boff + n * 2048 + k * 1024); } while (0)
; #define PG8_MMA(ai, bj, At, Bt) do { __builtin_amdgcn_s_setprio(1); _Pragma("unroll") for (int m = 0; m < 4; ++m) _Pragma("unroll") for (int n = 0; n < 2; ++n) _Pragma("unroll") for (int k = 0; k < 2; ++k) \
;         acc[ai][bj][m][n] = __builtin_amdgcn_mfma_f32_16x16x32_bf16(Bt[n][k], At[m][k], acc[ai][bj][m][n], 0, 0, 0); __builtin_amdgcn_s_setprio(0); } while (0)
; #define PG8_WAIT_V(n) asm volatile("s_waitcnt vmcnt(" #n ")" ::: "memory")
; #define PG8_WAIT_L(n) asm volatile("s_waitcnt lgkmcnt(" #n ")" ::: "memory")
; #define PG8_BAR __builtin_amdgcn_s_barrier()
; #define PG8_SCHED __builtin_amdgcn_sched_barrier(0)
; template <class Epi, class Sched, bool ALIGN_EPI = false, bool SP2 = false>
; __device__ __forceinline__ void gemm_phase(PG8_LAS unsigned char* lds, const Gemm g, const Sched& S, const Epi& E, int tid_in) {
;     ...
;             PG8_LDB(B0, 0, 0); PG8_LDB(B1, 0, 1); PG8_SCHED; PG8_LDA(At, 0, 0); PG8_STAGE(PG8_SA(1, 1), a1 + hstep, voffA);
;             PG8_WAIT_V(8); PG8_WAIT_L(0); PG8_BAR; PG8_MMA(0, 0, At, B0); PG8_MMA(0, 1, At, B1); PG8_BAR; PG8_SCHED;
;             PG8_LDA(At, 0, 1); PG8_STAGE(PG8_SB(0, 0), b2, voffB); PG8_STAGE(PG8_SB(0, 1), b2 + hstep, voffB); PG8_STAGE(PG8_SA(0, 0), a2, voffA);
;             PG8_WAIT_V(8); PG8_WAIT_L(0); PG8_BAR; PG8_MMA(1, 0, At, B0); PG8_MMA(1, 1, At, B1); PG8_BAR; PG8_SCHED;
.LBB0_508:
	v_or_b32_e32 v40, 0x10000, v215
	v_add_u32_e32 v44, 0x10400, v215
	v_add_u32_e32 v52, 0x10800, v215
	v_add_u32_e32 v60, 0x10c00, v215
	v_or_b32_e32 v146, 0x14000, v215
	v_add_u32_e32 v150, 0x14400, v215
	v_add_u32_e32 v154, 0x14800, v215
	v_add_u32_e32 v158, 0x14c00, v215
	s_add_i32 s44, s42, 2
	ds_read_b128 v[40:43], v40
	ds_read_b128 v[44:47], v44
	ds_read_b128 v[52:55], v52
	ds_read_b128 v[60:63], v60
	ds_read_b128 v[146:149], v146
	ds_read_b128 v[150:153], v150
	ds_read_b128 v[154:157], v154
	ds_read_b128 v[158:161], v158
	s_add_u32 s45, s40, 0x80
	s_addc_u32 s43, s41, 0
	s_cmp_eq_u32 s94, s42
	s_cselect_b32 s42, s88, s45
	s_cselect_b32 s43, s89, s43
	s_cselect_b32 s93, s91, s27
	s_cselect_b32 s92, s90, s26
	v_lshl_add_u64 v[218:219], s[40:41], 0, v[174:175]
	s_add_i32 m0, s57, 0xc000
	ds_read_b128 v[194:197], v214
	ds_read_b128 v[198:201], v214 offset:1024
	ds_read_b128 v[202:205], v214 offset:2048
	ds_read_b128 v[206:209], v214 offset:3072
	ds_read_b128 v[210:213], v214 offset:4096
	ds_read_b128 v[226:229], v214 offset:5120
	ds_read_b128 v[232:235], v214 offset:6144
	ds_read_b128 v[182:185], v214 offset:7168
	global_load_lds_dwordx4 v[218:219], off
	v_lshl_add_u64 v[218:219], s[40:41], 0, v[176:177]
	s_add_i32 m0, s57, 0xe000
	s_nop 0
	global_load_lds_dwordx4 v[218:219], off
	s_waitcnt vmcnt(8)
	s_waitcnt lgkmcnt(0)
	s_barrier
	s_setprio 1
	s_waitcnt lgkmcnt(0)
	v_mfma_f32_16x16x32_bf16 v[142:145], v[40:43], v[194:197], v[142:145]
	v_mfma_f32_16x16x32_bf16 v[138:141], v[52:55], v[194:197], v[138:141]
	v_mfma_f32_16x16x32_bf16 v[126:129], v[40:43], v[202:205], v[126:129]
	v_mfma_f32_16x16x32_bf16 v[122:125], v[52:55], v[202:205], v[122:125]
	v_mfma_f32_16x16x32_bf16 v[110:113], v[40:43], v[210:213], v[110:113]
	v_mfma_f32_16x16x32_bf16 v[106:109], v[52:55], v[210:213], v[106:109]
	v_mfma_f32_16x16x32_bf16 v[94:97], v[40:43], v[232:235], v[94:97]
	v_mfma_f32_16x16x32_bf16 v[90:93], v[52:55], v[232:235], v[90:93]
	v_mfma_f32_16x16x32_bf16 v[142:145], v[44:47], v[198:201], v[142:145]
	v_mfma_f32_16x16x32_bf16 v[138:141], v[60:63], v[198:201], v[138:141]
	v_mfma_f32_16x16x32_bf16 v[126:129], v[44:47], v[206:209], v[126:129]
	v_mfma_f32_16x16x32_bf16 v[122:125], v[60:63], v[206:209], v[122:125]
	v_mfma_f32_16x16x32_bf16 v[110:113], v[44:47], v[226:229], v[110:113]
	v_mfma_f32_16x16x32_bf16 v[106:109], v[60:63], v[226:229], v[106:109]
	v_mfma_f32_16x16x32_bf16 v[94:97], v[44:47], v[182:185], v[94:97]
	v_mfma_f32_16x16x32_bf16 v[90:93], v[60:63], v[182:185], v[90:93]
	s_setprio 0
	s_setprio 1
	v_mfma_f32_16x16x32_bf16 v[134:137], v[146:149], v[194:197], v[134:137]
	v_mfma_f32_16x16x32_bf16 v[130:133], v[154:157], v[194:197], v[130:133]
	v_mfma_f32_16x16x32_bf16 v[118:121], v[146:149], v[202:205], v[118:121]
	v_mfma_f32_16x16x32_bf16 v[114:117], v[154:157], v[202:205], v[114:117]
	v_mfma_f32_16x16x32_bf16 v[102:105], v[146:149], v[210:213], v[102:105]
	v_mfma_f32_16x16x32_bf16 v[98:101], v[154:157], v[210:213], v[98:101]
	v_mfma_f32_16x16x32_bf16 v[86:89], v[146:149], v[232:235], v[86:89]
	v_mfma_f32_16x16x32_bf16 v[82:85], v[154:157], v[232:235], v[82:85]
	v_mfma_f32_16x16x32_bf16 v[134:137], v[150:153], v[198:201], v[134:137]
	v_mfma_f32_16x16x32_bf16 v[130:133], v[158:161], v[198:201], v[130:133]
	v_mfma_f32_16x16x32_bf16 v[118:121], v[150:153], v[206:209], v[118:121]
	v_mfma_f32_16x16x32_bf16 v[114:117], v[158:161], v[206:209], v[114:117]
	v_mfma_f32_16x16x32_bf16 v[102:105], v[150:153], v[226:229], v[102:105]
	v_mfma_f32_16x16x32_bf16 v[98:101], v[158:161], v[226:229], v[98:101]
	v_mfma_f32_16x16x32_bf16 v[86:89], v[150:153], v[182:185], v[86:89]
	s_barrier
	v_mfma_f32_16x16x32_bf16 v[82:85], v[158:161], v[182:185], v[82:85]
	s_setprio 0
	s_mov_b32 m0, s95
	v_lshl_add_u64 v[218:219], s[92:93], 0, v[164:165]
	v_lshl_add_u64 v[250:251], s[92:93], 0, v[168:169]
	s_add_u32 s92, s92, s70
	ds_read_b128 v[182:185], v214 offset:16384
	ds_read_b128 v[194:197], v214 offset:17408
	ds_read_b128 v[198:201], v214 offset:18432
	ds_read_b128 v[202:205], v214 offset:19456
	ds_read_b128 v[206:209], v214 offset:20480
	ds_read_b128 v[210:213], v214 offset:21504
	ds_read_b128 v[226:229], v214 offset:22528
	ds_read_b128 v[232:235], v214 offset:23552
	global_load_lds_dwordx4 v[218:219], off
	s_mov_b32 m0, s31
	s_addc_u32 s93, s93, 0
	global_load_lds_dwordx4 v[250:251], off
	v_lshl_add_u64 v[236:237], s[92:93], 0, v[164:165]
	s_mov_b32 m0, s68
	v_lshl_add_u64 v[238:239], s[92:93], 0, v[168:169]
	global_load_lds_dwordx4 v[236:237], off
	s_mov_b32 m0, s69
	v_lshl_add_u64 v[240:241], s[42:43], 0, v[162:163]
	global_load_lds_dwordx4 v[238:239], off
	s_mov_b32 m0, s57
	v_lshl_add_u64 v[178:179], s[42:43], 0, v[166:167]
	global_load_lds_dwordx4 v[240:241], off
	s_mov_b32 m0, s29
	s_nop 0
	global_load_lds_dwordx4 v[178:179], off
	s_waitcnt vmcnt(8)
	s_waitcnt lgkmcnt(0)
	s_barrier
; #define PG8_STAGE(bufoff, gbase, voff) do { _Pragma("unroll") for (int _i = 0; _i < 2; ++_i) \
;         __builtin_amdgcn_global_load_lds((const unsigned*)((const char*)(gbase) + (voff)[_i]), (PG8_LAS unsigned*)(lds + (bufoff) + ldsw + _i * 8192), 16, 0, 0); } while (0)
; #define PG8_LDA(dst, b, h) do { _Pragma("unroll") for (int m = 0; m < 4; ++m) _Pragma("unroll") for (int k = 0; k < 2; ++k) dst[m][k] = *(const PG8_LAS bf16x8*)(lds + PG8_SA(b, h) + aoff + m * 2048 + k * 1024); } while (0)
; #define PG8_LDB(dst, b, h) do { _Pragma("unroll") for (int n = 0; n < 2; ++n) _Pragma("unroll") for (int k = 0; k < 2; ++k) dst[n][k] = *(const PG8_LAS bf16x8*)(lds + PG8_SB(b, h) + boff + n * 2048 + k * 1024); } while (0)
; #define PG8_MMA(ai, bj, At, Bt) do { __builtin_amdgcn_s_setprio(1); _Pragma("unroll") for (int m = 0; m < 4; ++m) _Pragma("unroll") for (int n = 0; n < 2; ++n) _Pragma("unroll") for (int k = 0; k < 2; ++k) \
;         acc[ai][bj][m][n] = __builtin_amdgcn_mfma_f32_16x16x32_bf16(Bt[n][k], At[m][k], acc[ai][bj][m][n], 0, 0, 0); __builtin_amdgcn_s_setprio(0); } while (0)
; #define PG8_WAIT_V(n) asm volatile("s_waitcnt vmcnt(" #n ")" ::: "memory")
; #define PG8_WAIT_L(n) asm volatile("s_waitcnt lgkmcnt(" #n ")" ::: "memory")
; #define PG8_BAR __builtin_amdgcn_s_barrier()
; #define PG8_SCHED __builtin_amdgcn_sched_barrier(0)
; template <class Epi, class Sched, bool ALIGN_EPI = false, bool SP2 = false>
; __device__ __forceinline__ void gemm_phase(PG8_LAS unsigned char* lds, const Gemm g, const Sched& S, const Epi& E, int tid_in) {
;     ...
;             PG8_WAIT_V(8); PG8_WAIT_L(0); PG8_BAR; PG8_MMA(1, 0, At, B0); PG8_MMA(1, 1, At, B1); PG8_BAR; PG8_SCHED;
;             PG8_LDB(B0, 1, 0); PG8_LDB(B1, 1, 1); PG8_SCHED; PG8_LDA(At, 1, 0); PG8_STAGE(PG8_SA(0, 1), a2 + hstep, voffA);
;             PG8_WAIT_V(8); PG8_WAIT_L(0); PG8_BAR; PG8_MMA(0, 0, At, B0); PG8_MMA(0, 1, At, B1); PG8_BAR; PG8_SCHED;
	s_setprio 1
	s_waitcnt lgkmcnt(0)
	v_mfma_f32_16x16x32_bf16 v[76:79], v[40:43], v[182:185], v[76:79]
	v_mfma_f32_16x16x32_bf16 v[72:75], v[52:55], v[182:185], v[72:75]
	v_mfma_f32_16x16x32_bf16 v[56:59], v[40:43], v[198:201], v[56:59]
	v_mfma_f32_16x16x32_bf16 v[48:51], v[52:55], v[198:201], v[48:51]
	v_mfma_f32_16x16x32_bf16 v[28:31], v[40:43], v[206:209], v[28:31]
	v_mfma_f32_16x16x32_bf16 v[24:27], v[52:55], v[206:209], v[24:27]
	v_mfma_f32_16x16x32_bf16 v[12:15], v[40:43], v[226:229], v[12:15]
	v_mfma_f32_16x16x32_bf16 v[8:11], v[52:55], v[226:229], v[8:11]
	v_mfma_f32_16x16x32_bf16 v[76:79], v[44:47], v[194:197], v[76:79]
	v_mfma_f32_16x16x32_bf16 v[72:75], v[60:63], v[194:197], v[72:75]
	v_mfma_f32_16x16x32_bf16 v[56:59], v[44:47], v[202:205], v[56:59]
	v_mfma_f32_16x16x32_bf16 v[48:51], v[60:63], v[202:205], v[48:51]
	v_mfma_f32_16x16x32_bf16 v[28:31], v[44:47], v[210:213], v[28:31]
	v_mfma_f32_16x16x32_bf16 v[24:27], v[60:63], v[210:213], v[24:27]
	v_mfma_f32_16x16x32_bf16 v[12:15], v[44:47], v[232:235], v[12:15]
	v_mfma_f32_16x16x32_bf16 v[8:11], v[60:63], v[232:235], v[8:11]
	s_setprio 0
	s_setprio 1
	v_mfma_f32_16x16x32_bf16 v[36:39], v[146:149], v[198:201], v[36:39]
	v_mfma_f32_16x16x32_bf16 v[32:35], v[154:157], v[198:201], v[32:35]
	v_mfma_f32_16x16x32_bf16 v[20:23], v[146:149], v[206:209], v[20:23]
	v_mfma_f32_16x16x32_bf16 v[16:19], v[154:157], v[206:209], v[16:19]
	v_mfma_f32_16x16x32_bf16 v[4:7], v[146:149], v[226:229], v[4:7]
	v_mfma_f32_16x16x32_bf16 v[0:3], v[154:157], v[226:229], v[0:3]
	v_mfma_f32_16x16x32_bf16 v[40:43], v[146:149], v[182:185], v[68:71]
	v_mfma_f32_16x16x32_bf16 v[44:47], v[154:157], v[182:185], v[64:67]
	v_mfma_f32_16x16x32_bf16 v[36:39], v[150:153], v[202:205], v[36:39]
	v_mfma_f32_16x16x32_bf16 v[32:35], v[158:161], v[202:205], v[32:35]
	v_mfma_f32_16x16x32_bf16 v[20:23], v[150:153], v[210:213], v[20:23]
	v_mfma_f32_16x16x32_bf16 v[16:19], v[158:161], v[210:213], v[16:19]
	v_mfma_f32_16x16x32_bf16 v[4:7], v[150:153], v[232:235], v[4:7]
	v_mfma_f32_16x16x32_bf16 v[0:3], v[158:161], v[232:235], v[0:3]
	v_mfma_f32_16x16x32_bf16 v[40:43], v[150:153], v[194:197], v[40:43]
	s_barrier
	v_mfma_f32_16x16x32_bf16 v[44:47], v[158:161], v[194:197], v[44:47]
	s_setprio 0
	v_or_b32_e32 v52, 0x18000, v215
	v_add_u32_e32 v60, 0x18400, v215
	v_add_u32_e32 v64, 0x18800, v215
	v_add_u32_e32 v68, 0x18c00, v215
	v_or_b32_e32 v146, 0x1c000, v215
	v_add_u32_e32 v150, 0x1c400, v215
	v_add_u32_e32 v154, 0x1c800, v215
	v_add_u32_e32 v158, 0x1cc00, v215
	ds_read_b128 v[52:55], v52
	ds_read_b128 v[60:63], v60
	ds_read_b128 v[64:67], v64
	ds_read_b128 v[68:71], v68
	ds_read_b128 v[146:149], v146
	ds_read_b128 v[150:153], v150
	ds_read_b128 v[154:157], v154
	ds_read_b128 v[158:161], v158
	s_add_u32 s42, s42, s70
	s_addc_u32 s43, s43, 0
	s_mov_b32 m0, s58
	v_lshl_add_u64 v[180:181], s[42:43], 0, v[162:163]
	ds_read_b128 v[182:185], v214 offset:32768
	ds_read_b128 v[194:197], v214 offset:33792
	ds_read_b128 v[198:201], v214 offset:34816
	ds_read_b128 v[202:205], v214 offset:35840
	ds_read_b128 v[206:209], v214 offset:36864
	ds_read_b128 v[210:213], v214 offset:37888
	ds_read_b128 v[226:229], v214 offset:38912
	ds_read_b128 v[232:235], v214 offset:39936
	global_load_lds_dwordx4 v[180:181], off
	v_lshl_add_u64 v[180:181], s[42:43], 0, v[166:167]
	s_mov_b32 m0, s59
	s_nop 0
	global_load_lds_dwordx4 v[180:181], off
	s_waitcnt vmcnt(8)
	s_waitcnt lgkmcnt(0)
	s_barrier
	s_setprio 1
	s_waitcnt lgkmcnt(0)
	v_mfma_f32_16x16x32_bf16 v[142:145], v[52:55], v[182:185], v[142:145]
	v_mfma_f32_16x16x32_bf16 v[138:141], v[64:67], v[182:185], v[138:141]
	v_mfma_f32_16x16x32_bf16 v[126:129], v[52:55], v[198:201], v[126:129]
	v_mfma_f32_16x16x32_bf16 v[122:125], v[64:67], v[198:201], v[122:125]
	v_mfma_f32_16x16x32_bf16 v[110:113], v[52:55], v[206:209], v[110:113]
	v_mfma_f32_16x16x32_bf16 v[106:109], v[64:67], v[206:209], v[106:109]
	v_mfma_f32_16x16x32_bf16 v[94:97], v[52:55], v[226:229], v[94:97]
	v_mfma_f32_16x16x32_bf16 v[90:93], v[64:67], v[226:229], v[90:93]
	v_mfma_f32_16x16x32_bf16 v[142:145], v[60:63], v[194:197], v[142:145]
	v_mfma_f32_16x16x32_bf16 v[138:141], v[68:71], v[194:197], v[138:141]
	v_mfma_f32_16x16x32_bf16 v[126:129], v[60:63], v[202:205], v[126:129]
	v_mfma_f32_16x16x32_bf16 v[122:125], v[68:71], v[202:205], v[122:125]
	v_mfma_f32_16x16x32_bf16 v[110:113], v[60:63], v[210:213], v[110:113]
	v_mfma_f32_16x16x32_bf16 v[106:109], v[68:71], v[210:213], v[106:109]
	v_mfma_f32_16x16x32_bf16 v[94:97], v[60:63], v[232:235], v[94:97]
	v_mfma_f32_16x16x32_bf16 v[90:93], v[68:71], v[232:235], v[90:93]
	s_setprio 0
	s_setprio 1
	v_mfma_f32_16x16x32_bf16 v[134:137], v[146:149], v[182:185], v[134:137]
	v_mfma_f32_16x16x32_bf16 v[130:133], v[154:157], v[182:185], v[130:133]
	v_mfma_f32_16x16x32_bf16 v[118:121], v[146:149], v[198:201], v[118:121]
	v_mfma_f32_16x16x32_bf16 v[114:117], v[154:157], v[198:201], v[114:117]
	v_mfma_f32_16x16x32_bf16 v[102:105], v[146:149], v[206:209], v[102:105]
	v_mfma_f32_16x16x32_bf16 v[98:101], v[154:157], v[206:209], v[98:101]
	v_mfma_f32_16x16x32_bf16 v[86:89], v[146:149], v[226:229], v[86:89]
	v_mfma_f32_16x16x32_bf16 v[82:85], v[154:157], v[226:229], v[82:85]
	v_mfma_f32_16x16x32_bf16 v[134:137], v[150:153], v[194:197], v[134:137]
	v_mfma_f32_16x16x32_bf16 v[130:133], v[158:161], v[194:197], v[130:133]
	v_mfma_f32_16x16x32_bf16 v[118:121], v[150:153], v[202:205], v[118:121]
	v_mfma_f32_16x16x32_bf16 v[114:117], v[158:161], v[202:205], v[114:117]
	v_mfma_f32_16x16x32_bf16 v[102:105], v[150:153], v[210:213], v[102:105]
	v_mfma_f32_16x16x32_bf16 v[98:101], v[158:161], v[210:213], v[98:101]
	v_mfma_f32_16x16x32_bf16 v[86:89], v[150:153], v[232:235], v[86:89]
	s_barrier
; #define PG8_STAGE(bufoff, gbase, voff) do { _Pragma("unroll") for (int _i = 0; _i < 2; ++_i) \
;         __builtin_amdgcn_global_load_lds((const unsigned*)((const char*)(gbase) + (voff)[_i]), (PG8_LAS unsigned*)(lds + (bufoff) + ldsw + _i * 8192), 16, 0, 0); } while (0)
; #define PG8_LDA(dst, b, h) do { _Pragma("unroll") for (int m = 0; m < 4; ++m) _Pragma("unroll") for (int k = 0; k < 2; ++k) dst[m][k] = *(const PG8_LAS bf16x8*)(lds + PG8_SA(b, h) + aoff + m * 2048 + k * 1024); } while (0)
; #define PG8_MMA(ai, bj, At, Bt) do { __builtin_amdgcn_s_setprio(1); _Pragma("unroll") for (int m = 0; m < 4; ++m) _Pragma("unroll") for (int n = 0; n < 2; ++n) _Pragma("unroll") for (int k = 0; k < 2; ++k) \
;         acc[ai][bj][m][n] = __builtin_amdgcn_mfma_f32_16x16x32_bf16(Bt[n][k], At[m][k], acc[ai][bj][m][n], 0, 0, 0); __builtin_amdgcn_s_setprio(0); } while (0)
; #define PG8_WAIT_V(n) asm volatile("s_waitcnt vmcnt(" #n ")" ::: "memory")
; #define PG8_WAIT_L(n) asm volatile("s_waitcnt lgkmcnt(" #n ")" ::: "memory")
; #define PG8_BAR __builtin_amdgcn_s_barrier()
; #define PG8_SCHED __builtin_amdgcn_sched_barrier(0)
; template <class Epi, class Sched, bool ALIGN_EPI = false, bool SP2 = false>
; __device__ __forceinline__ void gemm_phase(PG8_LAS unsigned char* lds, const Gemm g, const Sched& S, const Epi& E, int tid_in) {
;     ...
;             PG8_LDA(At, 1, 1); PG8_STAGE(PG8_SB(1, 0), b3, voffB); PG8_STAGE(PG8_SB(1, 1), b3 + hstep, voffB); PG8_STAGE(PG8_SA(1, 0), a3, voffA);
;             PG8_WAIT_V(8); PG8_WAIT_L(0); PG8_BAR; PG8_MMA(1, 0, At, B0); PG8_MMA(1, 1, At, B1); PG8_BAR; PG8_SCHED;
;     ...
;         if constexpr (ALIGN_EPI) { if (wr == 0) PG8_BAR; }
	v_mfma_f32_16x16x32_bf16 v[82:85], v[158:161], v[232:235], v[82:85]
	s_setprio 0
	s_mov_b32 m0, s64
	v_lshl_add_u64 v[180:181], v[218:219], 0, s[48:49]
	ds_read_b128 v[182:185], v214 offset:49152
	ds_read_b128 v[194:197], v214 offset:50176
	ds_read_b128 v[198:201], v214 offset:51200
	ds_read_b128 v[202:205], v214 offset:52224
	ds_read_b128 v[206:209], v214 offset:53248
	ds_read_b128 v[210:213], v214 offset:54272
	ds_read_b128 v[226:229], v214 offset:55296
	ds_read_b128 v[232:235], v214 offset:56320
	global_load_lds_dwordx4 v[180:181], off
	v_lshl_add_u64 v[180:181], v[250:251], 0, s[48:49]
	s_mov_b32 m0, s65
	v_lshl_add_u64 v[178:179], v[178:179], 0, s[48:49]
	global_load_lds_dwordx4 v[180:181], off
	v_lshl_add_u64 v[180:181], v[236:237], 0, s[48:49]
	s_mov_b32 m0, s61
	s_nop 0
	global_load_lds_dwordx4 v[180:181], off
	v_lshl_add_u64 v[180:181], v[238:239], 0, s[48:49]
	s_mov_b32 m0, s62
	s_nop 0
	global_load_lds_dwordx4 v[180:181], off
	v_lshl_add_u64 v[180:181], v[240:241], 0, s[48:49]
	s_mov_b32 m0, s72
	s_nop 0
	global_load_lds_dwordx4 v[180:181], off
	s_mov_b32 m0, s73
	s_nop 0
	global_load_lds_dwordx4 v[178:179], off
	s_waitcnt vmcnt(8)
	s_waitcnt lgkmcnt(0)
	s_barrier
	s_setprio 1
	s_waitcnt lgkmcnt(0)
	v_mfma_f32_16x16x32_bf16 v[76:79], v[52:55], v[182:185], v[76:79]
	v_mfma_f32_16x16x32_bf16 v[72:75], v[64:67], v[182:185], v[72:75]
	v_mfma_f32_16x16x32_bf16 v[56:59], v[52:55], v[198:201], v[56:59]
	v_mfma_f32_16x16x32_bf16 v[48:51], v[64:67], v[198:201], v[48:51]
	v_mfma_f32_16x16x32_bf16 v[28:31], v[52:55], v[206:209], v[28:31]
	v_mfma_f32_16x16x32_bf16 v[24:27], v[64:67], v[206:209], v[24:27]
	v_mfma_f32_16x16x32_bf16 v[12:15], v[52:55], v[226:229], v[12:15]
	v_mfma_f32_16x16x32_bf16 v[8:11], v[64:67], v[226:229], v[8:11]
	v_mfma_f32_16x16x32_bf16 v[76:79], v[60:63], v[194:197], v[76:79]
	v_mfma_f32_16x16x32_bf16 v[72:75], v[68:71], v[194:197], v[72:75]
	v_mfma_f32_16x16x32_bf16 v[56:59], v[60:63], v[202:205], v[56:59]
	v_mfma_f32_16x16x32_bf16 v[48:51], v[68:71], v[202:205], v[48:51]
	v_mfma_f32_16x16x32_bf16 v[28:31], v[60:63], v[210:213], v[28:31]
	v_mfma_f32_16x16x32_bf16 v[24:27], v[68:71], v[210:213], v[24:27]
	v_mfma_f32_16x16x32_bf16 v[12:15], v[60:63], v[232:235], v[12:15]
	v_mfma_f32_16x16x32_bf16 v[8:11], v[68:71], v[232:235], v[8:11]
	s_setprio 0
	s_setprio 1
	v_mfma_f32_16x16x32_bf16 v[40:43], v[146:149], v[182:185], v[40:43]
	v_mfma_f32_16x16x32_bf16 v[68:71], v[150:153], v[194:197], v[40:43]
	v_mfma_f32_16x16x32_bf16 v[40:43], v[154:157], v[182:185], v[44:47]
	v_mfma_f32_16x16x32_bf16 v[36:39], v[146:149], v[198:201], v[36:39]
	v_mfma_f32_16x16x32_bf16 v[32:35], v[154:157], v[198:201], v[32:35]
	v_mfma_f32_16x16x32_bf16 v[20:23], v[146:149], v[206:209], v[20:23]
	v_mfma_f32_16x16x32_bf16 v[16:19], v[154:157], v[206:209], v[16:19]
	v_mfma_f32_16x16x32_bf16 v[4:7], v[146:149], v[226:229], v[4:7]
	v_mfma_f32_16x16x32_bf16 v[0:3], v[154:157], v[226:229], v[0:3]
	v_mfma_f32_16x16x32_bf16 v[64:67], v[158:161], v[194:197], v[40:43]
	v_mfma_f32_16x16x32_bf16 v[36:39], v[150:153], v[202:205], v[36:39]
	v_mfma_f32_16x16x32_bf16 v[32:35], v[158:161], v[202:205], v[32:35]
	v_mfma_f32_16x16x32_bf16 v[20:23], v[150:153], v[210:213], v[20:23]
	v_mfma_f32_16x16x32_bf16 v[16:19], v[158:161], v[210:213], v[16:19]
	v_mfma_f32_16x16x32_bf16 v[4:7], v[150:153], v[232:235], v[4:7]
	s_barrier
	v_mfma_f32_16x16x32_bf16 v[0:3], v[158:161], v[232:235], v[0:3]
	s_setprio 0
	s_add_u32 s40, s40, 0x100
	s_addc_u32 s41, s41, 0
	s_add_u32 s26, s26, 0x100
	s_addc_u32 s27, s27, 0
	s_cmp_ge_u32 s44, s66
	s_mov_b32 s42, s44
	s_cbranch_scc0 .LBB0_508
	s_and_b64 vcc, exec, s[78:79]
	s_cbranch_vccz .Ltrail_511
	s_barrier
	s_branch .LBB0_511

; #define PG8_STAGE(bufoff, gbase, voff) do { _Pragma("unroll") for (int _i = 0; _i < 2; ++_i) \
;         __builtin_amdgcn_global_load_lds((const unsigned*)((const char*)(gbase) + (voff)[_i]), (PG8_LAS unsigned*)(lds + (bufoff) + ldsw + _i * 8192), 16, 0, 0); } while (0)
; #define PG8_LDA(dst, b, h) do { _Pragma("unroll") for (int m = 0; m < 4; ++m) _Pragma("unroll") for (int k = 0; k < 2; ++k) dst[m][k] = *(const PG8_LAS bf16x8*)(lds + PG8_SA(b, h) + aoff + m * 2048 + k * 1024); } while (0)
; #define PG8_LDB(dst, b, h) do { _Pragma("unroll") for (int n = 0; n < 2; ++n) _Pragma("unroll") for (int k = 0; k < 2; ++k) dst[n][k] = *(const PG8_LAS bf16x8*)(lds + PG8_SB(b, h) + boff + n * 2048 + k * 1024); } while (0)
; #define PG8_MMA(ai, bj, At, Bt) do { __builtin_amdgcn_s_setprio(1); _Pragma("unroll") for (int m = 0; m < 4; ++m) _Pragma("unroll") for (int n = 0; n < 2; ++n) _Pragma("unroll") for (int k = 0; k < 2; ++k) \
;         acc[ai][bj][m][n] = __builtin_amdgcn_mfma_f32_16x16x32_bf16(Bt[n][k], At[m][k], acc[ai][bj][m][n], 0, 0, 0); __builtin_amdgcn_s_setprio(0); } while (0)
; #define PG8_WAIT_V(n) asm volatile("s_waitcnt vmcnt(" #n ")" ::: "memory")
; #define PG8_WAIT_L(n) asm volatile("s_waitcnt lgkmcnt(" #n ")" ::: "memory")
; #define PG8_BAR __builtin_amdgcn_s_barrier()
; #define PG8_SCHED __builtin_amdgcn_sched_barrier(0)
; template <class Epi, class Sched, bool ALIGN_EPI = false, bool SP2 = false>
; __device__ __forceinline__ void gemm_phase(PG8_LAS unsigned char* lds, const Gemm g, const Sched& S, const Epi& E, int tid_in) {
;     ...
;             PG8_LDB(B0, 0, 0); PG8_LDB(B1, 0, 1); PG8_SCHED; PG8_LDA(At, 0, 0); PG8_STAGE(PG8_SA(1, 1), a1 + hstep, voffA);
;             PG8_WAIT_V(8); PG8_WAIT_L(0); PG8_BAR; PG8_MMA(0, 0, At, B0); PG8_MMA(0, 1, At, B1); PG8_BAR; PG8_SCHED;
;             PG8_LDA(At, 0, 1); PG8_STAGE(PG8_SB(0, 0), b2, voffB); PG8_STAGE(PG8_SB(0, 1), b2 + hstep, voffB); PG8_STAGE(PG8_SA(0, 0), a2, voffA);
;             PG8_WAIT_V(8); PG8_WAIT_L(0); PG8_BAR; PG8_MMA(1, 0, At, B0); PG8_MMA(1, 1, At, B1); PG8_BAR; PG8_SCHED;
.LBB0_780:
	v_or_b32_e32 v142, 0x10000, v145
	v_add_u32_e32 v143, 0x10400, v145
	ds_read_b128 v[148:151], v142
	ds_read_b128 v[152:155], v143
	v_add_u32_e32 v142, 0x10800, v145
	v_add_u32_e32 v143, 0x10c00, v145
	ds_read_b128 v[156:159], v142
	ds_read_b128 v[160:163], v143
	v_or_b32_e32 v142, 0x14000, v145
	v_add_u32_e32 v143, 0x14400, v145
	ds_read_b128 v[164:167], v142
	ds_read_b128 v[168:171], v143
	v_add_u32_e32 v142, 0x14800, v145
	v_add_u32_e32 v143, 0x14c00, v145
	ds_read_b128 v[172:175], v142
	ds_read_b128 v[194:197], v143
	s_add_u32 s70, s68, 0xfffc0080
	s_addc_u32 s71, s69, -1
	s_cmp_eq_u32 s82, 12
	s_cselect_b32 s73, s45, s71
	s_cselect_b32 s72, s78, s70
	s_cselect_b32 s71, s43, s81
	s_cselect_b32 s70, s79, s80
	v_lshl_add_u64 v[142:143], s[68:69], 0, v[138:139]
	s_add_i32 m0, s22, 0xc000
	ds_read_b128 v[198:201], v144
	ds_read_b128 v[202:205], v144 offset:1024
	ds_read_b128 v[206:209], v144 offset:2048
	ds_read_b128 v[210:213], v144 offset:3072
	ds_read_b128 v[214:217], v144 offset:4096
	ds_read_b128 v[248:251], v144 offset:5120
	ds_read_b128 v[232:235], v144 offset:6144
	ds_read_b128 v[226:229], v144 offset:7168
	global_load_lds_dwordx4 v[142:143], off
	v_lshl_add_u64 v[142:143], s[68:69], 0, v[140:141]
	s_add_i32 m0, s22, 0xe000
	s_nop 0
	global_load_lds_dwordx4 v[142:143], off
	s_waitcnt vmcnt(8)
	s_waitcnt lgkmcnt(0)
	s_barrier
	s_setprio 1
	s_waitcnt lgkmcnt(0)
	v_mfma_f32_16x16x32_bf16 v[126:129], v[148:151], v[198:201], v[126:129]
	v_mfma_f32_16x16x32_bf16 v[118:121], v[156:159], v[198:201], v[118:121]
	v_mfma_f32_16x16x32_bf16 v[110:113], v[148:151], v[206:209], v[110:113]
	v_mfma_f32_16x16x32_bf16 v[102:105], v[156:159], v[206:209], v[102:105]
	v_mfma_f32_16x16x32_bf16 v[94:97], v[148:151], v[214:217], v[94:97]
	v_mfma_f32_16x16x32_bf16 v[86:89], v[156:159], v[214:217], v[86:89]
	v_mfma_f32_16x16x32_bf16 v[76:79], v[148:151], v[232:235], v[76:79]
	v_mfma_f32_16x16x32_bf16 v[68:71], v[156:159], v[232:235], v[68:71]
	v_mfma_f32_16x16x32_bf16 v[126:129], v[152:155], v[202:205], v[126:129]
	v_mfma_f32_16x16x32_bf16 v[118:121], v[160:163], v[202:205], v[118:121]
	v_mfma_f32_16x16x32_bf16 v[110:113], v[152:155], v[210:213], v[110:113]
	v_mfma_f32_16x16x32_bf16 v[102:105], v[160:163], v[210:213], v[102:105]
	v_mfma_f32_16x16x32_bf16 v[94:97], v[152:155], v[248:251], v[94:97]
	v_mfma_f32_16x16x32_bf16 v[86:89], v[160:163], v[248:251], v[86:89]
	v_mfma_f32_16x16x32_bf16 v[76:79], v[152:155], v[226:229], v[76:79]
	v_mfma_f32_16x16x32_bf16 v[68:71], v[160:163], v[226:229], v[68:71]
	s_setprio 0
	s_setprio 1
	v_mfma_f32_16x16x32_bf16 v[122:125], v[164:167], v[198:201], v[122:125]
	v_mfma_f32_16x16x32_bf16 v[114:117], v[172:175], v[198:201], v[114:117]
	v_mfma_f32_16x16x32_bf16 v[106:109], v[164:167], v[206:209], v[106:109]
	v_mfma_f32_16x16x32_bf16 v[98:101], v[172:175], v[206:209], v[98:101]
	v_mfma_f32_16x16x32_bf16 v[90:93], v[164:167], v[214:217], v[90:93]
	v_mfma_f32_16x16x32_bf16 v[82:85], v[172:175], v[214:217], v[82:85]
	v_mfma_f32_16x16x32_bf16 v[72:75], v[164:167], v[232:235], v[72:75]
	v_mfma_f32_16x16x32_bf16 v[64:67], v[172:175], v[232:235], v[64:67]
	v_mfma_f32_16x16x32_bf16 v[122:125], v[168:171], v[202:205], v[122:125]
	v_mfma_f32_16x16x32_bf16 v[114:117], v[194:197], v[202:205], v[114:117]
	v_mfma_f32_16x16x32_bf16 v[106:109], v[168:171], v[210:213], v[106:109]
	v_mfma_f32_16x16x32_bf16 v[98:101], v[194:197], v[210:213], v[98:101]
	v_mfma_f32_16x16x32_bf16 v[90:93], v[168:171], v[248:251], v[90:93]
	v_mfma_f32_16x16x32_bf16 v[82:85], v[194:197], v[248:251], v[82:85]
	v_mfma_f32_16x16x32_bf16 v[72:75], v[168:171], v[226:229], v[72:75]
	s_barrier
	v_mfma_f32_16x16x32_bf16 v[64:67], v[194:197], v[226:229], v[64:67]
	s_setprio 0
	s_mov_b32 m0, s24
	v_lshl_add_u64 v[142:143], s[70:71], 0, v[134:135]
	s_add_u32 s84, s70, 0x40000
	ds_read_b128 v[198:201], v144 offset:16384
	ds_read_b128 v[202:205], v144 offset:17408
	ds_read_b128 v[206:209], v144 offset:18432
	ds_read_b128 v[210:213], v144 offset:19456
	ds_read_b128 v[214:217], v144 offset:20480
	ds_read_b128 v[226:229], v144 offset:21504
	ds_read_b128 v[232:235], v144 offset:22528
	ds_read_b128 v[248:251], v144 offset:23552
	global_load_lds_dwordx4 v[142:143], off
	v_lshl_add_u64 v[176:177], s[70:71], 0, v[130:131]
	s_mov_b32 m0, s25
	s_addc_u32 s85, s71, 0
	global_load_lds_dwordx4 v[176:177], off
	v_lshl_add_u64 v[182:183], s[84:85], 0, v[134:135]
	s_mov_b32 m0, s26
	v_lshl_add_u64 v[184:185], s[72:73], 0, v[132:133]
	global_load_lds_dwordx4 v[182:183], off
	v_lshl_add_u64 v[182:183], s[84:85], 0, v[130:131]
	s_mov_b32 m0, s27
	s_nop 0
	global_load_lds_dwordx4 v[182:183], off
	v_lshl_add_u64 v[182:183], s[72:73], 0, v[136:137]
	s_mov_b32 m0, s22
	s_nop 0
	global_load_lds_dwordx4 v[182:183], off
	s_mov_b32 m0, s29
	s_nop 0
	global_load_lds_dwordx4 v[184:185], off
	s_waitcnt vmcnt(8)
	s_waitcnt lgkmcnt(0)
	s_barrier
; #define PG8_STAGE(bufoff, gbase, voff) do { _Pragma("unroll") for (int _i = 0; _i < 2; ++_i) \
;         __builtin_amdgcn_global_load_lds((const unsigned*)((const char*)(gbase) + (voff)[_i]), (PG8_LAS unsigned*)(lds + (bufoff) + ldsw + _i * 8192), 16, 0, 0); } while (0)
; #define PG8_LDA(dst, b, h) do { _Pragma("unroll") for (int m = 0; m < 4; ++m) _Pragma("unroll") for (int k = 0; k < 2; ++k) dst[m][k] = *(const PG8_LAS bf16x8*)(lds + PG8_SA(b, h) + aoff + m * 2048 + k * 1024); } while (0)
; #define PG8_LDB(dst, b, h) do { _Pragma("unroll") for (int n = 0; n < 2; ++n) _Pragma("unroll") for (int k = 0; k < 2; ++k) dst[n][k] = *(const PG8_LAS bf16x8*)(lds + PG8_SB(b, h) + boff + n * 2048 + k * 1024); } while (0)
; #define PG8_MMA(ai, bj, At, Bt) do { __builtin_amdgcn_s_setprio(1); _Pragma("unroll") for (int m = 0; m < 4; ++m) _Pragma("unroll") for (int n = 0; n < 2; ++n) _Pragma("unroll") for (int k = 0; k < 2; ++k) \
;         acc[ai][bj][m][n] = __builtin_amdgcn_mfma_f32_16x16x32_bf16(Bt[n][k], At[m][k], acc[ai][bj][m][n], 0, 0, 0); __builtin_amdgcn_s_setprio(0); } while (0)
; #define PG8_WAIT_V(n) asm volatile("s_waitcnt vmcnt(" #n ")" ::: "memory")
; #define PG8_WAIT_L(n) asm volatile("s_waitcnt lgkmcnt(" #n ")" ::: "memory")
; #define PG8_BAR __builtin_amdgcn_s_barrier()
; #define PG8_SCHED __builtin_amdgcn_sched_barrier(0)
; template <class Epi, class Sched, bool ALIGN_EPI = false, bool SP2 = false>
; __device__ __forceinline__ void gemm_phase(PG8_LAS unsigned char* lds, const Gemm g, const Sched& S, const Epi& E, int tid_in) {
;     ...
;             PG8_WAIT_V(8); PG8_WAIT_L(0); PG8_BAR; PG8_MMA(1, 0, At, B0); PG8_MMA(1, 1, At, B1); PG8_BAR; PG8_SCHED;
;             PG8_LDB(B0, 1, 0); PG8_LDB(B1, 1, 1); PG8_SCHED; PG8_LDA(At, 1, 0); PG8_STAGE(PG8_SA(0, 1), a2 + hstep, voffA);
;             PG8_WAIT_V(8); PG8_WAIT_L(0); PG8_BAR; PG8_MMA(0, 0, At, B0); PG8_MMA(0, 1, At, B1); PG8_BAR; PG8_SCHED;
	s_setprio 1
	s_waitcnt lgkmcnt(0)
	v_mfma_f32_16x16x32_bf16 v[60:63], v[148:151], v[198:201], v[60:63]
	v_mfma_f32_16x16x32_bf16 v[52:55], v[156:159], v[198:201], v[52:55]
	v_mfma_f32_16x16x32_bf16 v[44:47], v[148:151], v[206:209], v[44:47]
	v_mfma_f32_16x16x32_bf16 v[36:39], v[156:159], v[206:209], v[36:39]
	v_mfma_f32_16x16x32_bf16 v[28:31], v[148:151], v[214:217], v[28:31]
	v_mfma_f32_16x16x32_bf16 v[20:23], v[156:159], v[214:217], v[20:23]
	v_mfma_f32_16x16x32_bf16 v[12:15], v[148:151], v[232:235], v[12:15]
	v_mfma_f32_16x16x32_bf16 v[4:7], v[156:159], v[232:235], v[4:7]
	v_mfma_f32_16x16x32_bf16 v[60:63], v[152:155], v[202:205], v[60:63]
	v_mfma_f32_16x16x32_bf16 v[52:55], v[160:163], v[202:205], v[52:55]
	v_mfma_f32_16x16x32_bf16 v[44:47], v[152:155], v[210:213], v[44:47]
	v_mfma_f32_16x16x32_bf16 v[36:39], v[160:163], v[210:213], v[36:39]
	v_mfma_f32_16x16x32_bf16 v[28:31], v[152:155], v[226:229], v[28:31]
	v_mfma_f32_16x16x32_bf16 v[20:23], v[160:163], v[226:229], v[20:23]
	v_mfma_f32_16x16x32_bf16 v[12:15], v[152:155], v[248:251], v[12:15]
	v_mfma_f32_16x16x32_bf16 v[4:7], v[160:163], v[248:251], v[4:7]
	s_setprio 0
	s_setprio 1
	v_mfma_f32_16x16x32_bf16 v[56:59], v[164:167], v[198:201], v[56:59]
	v_mfma_f32_16x16x32_bf16 v[48:51], v[172:175], v[198:201], v[48:51]
	v_mfma_f32_16x16x32_bf16 v[40:43], v[164:167], v[206:209], v[40:43]
	v_mfma_f32_16x16x32_bf16 v[32:35], v[172:175], v[206:209], v[32:35]
	v_mfma_f32_16x16x32_bf16 v[24:27], v[164:167], v[214:217], v[24:27]
	v_mfma_f32_16x16x32_bf16 v[16:19], v[172:175], v[214:217], v[16:19]
	v_mfma_f32_16x16x32_bf16 v[8:11], v[164:167], v[232:235], v[8:11]
	v_mfma_f32_16x16x32_bf16 v[0:3], v[172:175], v[232:235], v[0:3]
	v_mfma_f32_16x16x32_bf16 v[56:59], v[168:171], v[202:205], v[56:59]
	v_mfma_f32_16x16x32_bf16 v[48:51], v[194:197], v[202:205], v[48:51]
	v_mfma_f32_16x16x32_bf16 v[40:43], v[168:171], v[210:213], v[40:43]
	v_mfma_f32_16x16x32_bf16 v[32:35], v[194:197], v[210:213], v[32:35]
	v_mfma_f32_16x16x32_bf16 v[24:27], v[168:171], v[226:229], v[24:27]
	v_mfma_f32_16x16x32_bf16 v[16:19], v[194:197], v[226:229], v[16:19]
	v_mfma_f32_16x16x32_bf16 v[8:11], v[168:171], v[248:251], v[8:11]
	s_barrier
	v_mfma_f32_16x16x32_bf16 v[0:3], v[194:197], v[248:251], v[0:3]
	s_setprio 0
	v_or_b32_e32 v148, 0x18000, v145
	v_add_u32_e32 v152, 0x18400, v145
	v_add_u32_e32 v156, 0x18800, v145
	v_add_u32_e32 v160, 0x18c00, v145
	v_or_b32_e32 v164, 0x1c000, v145
	v_add_u32_e32 v168, 0x1c400, v145
	v_add_u32_e32 v172, 0x1c800, v145
	ds_read_b128 v[148:151], v148
	ds_read_b128 v[152:155], v152
	ds_read_b128 v[156:159], v156
	ds_read_b128 v[160:163], v160
	ds_read_b128 v[164:167], v164
	ds_read_b128 v[168:171], v168
	v_add_u32_e32 v178, 0x1cc00, v145
	ds_read_b128 v[172:175], v172
	ds_read_b128 v[194:197], v178
	s_add_u32 s72, s72, 0x40000
	s_addc_u32 s73, s73, 0
	s_mov_b32 m0, s31
	v_lshl_add_u64 v[218:219], s[72:73], 0, v[136:137]
	ds_read_b128 v[198:201], v144 offset:32768
	ds_read_b128 v[202:205], v144 offset:33792
	ds_read_b128 v[206:209], v144 offset:34816
	ds_read_b128 v[210:213], v144 offset:35840
	ds_read_b128 v[214:217], v144 offset:36864
	ds_read_b128 v[226:229], v144 offset:37888
	ds_read_b128 v[232:235], v144 offset:38912
	ds_read_b128 v[248:251], v144 offset:39936
	global_load_lds_dwordx4 v[218:219], off
	v_lshl_add_u64 v[218:219], s[72:73], 0, v[132:133]
	s_mov_b32 m0, s57
	s_nop 0
	global_load_lds_dwordx4 v[218:219], off
	s_waitcnt vmcnt(8)
	s_waitcnt lgkmcnt(0)
	s_barrier
	s_setprio 1
	s_waitcnt lgkmcnt(0)
	v_mfma_f32_16x16x32_bf16 v[126:129], v[148:151], v[198:201], v[126:129]
	v_mfma_f32_16x16x32_bf16 v[118:121], v[156:159], v[198:201], v[118:121]
	v_mfma_f32_16x16x32_bf16 v[110:113], v[148:151], v[206:209], v[110:113]
	v_mfma_f32_16x16x32_bf16 v[102:105], v[156:159], v[206:209], v[102:105]
	v_mfma_f32_16x16x32_bf16 v[94:97], v[148:151], v[214:217], v[94:97]
	v_mfma_f32_16x16x32_bf16 v[86:89], v[156:159], v[214:217], v[86:89]
	v_mfma_f32_16x16x32_bf16 v[76:79], v[148:151], v[232:235], v[76:79]
	v_mfma_f32_16x16x32_bf16 v[68:71], v[156:159], v[232:235], v[68:71]
	v_mfma_f32_16x16x32_bf16 v[126:129], v[152:155], v[202:205], v[126:129]
	v_mfma_f32_16x16x32_bf16 v[118:121], v[160:163], v[202:205], v[118:121]
	v_mfma_f32_16x16x32_bf16 v[110:113], v[152:155], v[210:213], v[110:113]
	v_mfma_f32_16x16x32_bf16 v[102:105], v[160:163], v[210:213], v[102:105]
	v_mfma_f32_16x16x32_bf16 v[94:97], v[152:155], v[226:229], v[94:97]
	v_mfma_f32_16x16x32_bf16 v[86:89], v[160:163], v[226:229], v[86:89]
	v_mfma_f32_16x16x32_bf16 v[76:79], v[152:155], v[248:251], v[76:79]
	v_mfma_f32_16x16x32_bf16 v[68:71], v[160:163], v[248:251], v[68:71]
	s_setprio 0
	s_setprio 1
	v_mfma_f32_16x16x32_bf16 v[122:125], v[164:167], v[198:201], v[122:125]
	v_mfma_f32_16x16x32_bf16 v[114:117], v[172:175], v[198:201], v[114:117]
	v_mfma_f32_16x16x32_bf16 v[106:109], v[164:167], v[206:209], v[106:109]
	v_mfma_f32_16x16x32_bf16 v[98:101], v[172:175], v[206:209], v[98:101]
	v_mfma_f32_16x16x32_bf16 v[90:93], v[164:167], v[214:217], v[90:93]
	v_mfma_f32_16x16x32_bf16 v[82:85], v[172:175], v[214:217], v[82:85]
	v_mfma_f32_16x16x32_bf16 v[72:75], v[164:167], v[232:235], v[72:75]
	v_mfma_f32_16x16x32_bf16 v[64:67], v[172:175], v[232:235], v[64:67]
	v_mfma_f32_16x16x32_bf16 v[122:125], v[168:171], v[202:205], v[122:125]
	v_mfma_f32_16x16x32_bf16 v[114:117], v[194:197], v[202:205], v[114:117]
	v_mfma_f32_16x16x32_bf16 v[106:109], v[168:171], v[210:213], v[106:109]
	v_mfma_f32_16x16x32_bf16 v[98:101], v[194:197], v[210:213], v[98:101]
	v_mfma_f32_16x16x32_bf16 v[90:93], v[168:171], v[226:229], v[90:93]
	v_mfma_f32_16x16x32_bf16 v[82:85], v[194:197], v[226:229], v[82:85]
	v_mfma_f32_16x16x32_bf16 v[72:75], v[168:171], v[248:251], v[72:75]
	s_barrier
; #define PG8_STAGE(bufoff, gbase, voff) do { _Pragma("unroll") for (int _i = 0; _i < 2; ++_i) \
;         __builtin_amdgcn_global_load_lds((const unsigned*)((const char*)(gbase) + (voff)[_i]), (PG8_LAS unsigned*)(lds + (bufoff) + ldsw + _i * 8192), 16, 0, 0); } while (0)
; #define PG8_LDA(dst, b, h) do { _Pragma("unroll") for (int m = 0; m < 4; ++m) _Pragma("unroll") for (int k = 0; k < 2; ++k) dst[m][k] = *(const PG8_LAS bf16x8*)(lds + PG8_SA(b, h) + aoff + m * 2048 + k * 1024); } while (0)
; #define PG8_MMA(ai, bj, At, Bt) do { __builtin_amdgcn_s_setprio(1); _Pragma("unroll") for (int m = 0; m < 4; ++m) _Pragma("unroll") for (int n = 0; n < 2; ++n) _Pragma("unroll") for (int k = 0; k < 2; ++k) \
;         acc[ai][bj][m][n] = __builtin_amdgcn_mfma_f32_16x16x32_bf16(Bt[n][k], At[m][k], acc[ai][bj][m][n], 0, 0, 0); __builtin_amdgcn_s_setprio(0); } while (0)
; #define PG8_WAIT_V(n) asm volatile("s_waitcnt vmcnt(" #n ")" ::: "memory")
; #define PG8_WAIT_L(n) asm volatile("s_waitcnt lgkmcnt(" #n ")" ::: "memory")
; #define PG8_BAR __builtin_amdgcn_s_barrier()
; #define PG8_SCHED __builtin_amdgcn_sched_barrier(0)
; template <class Epi, class Sched, bool ALIGN_EPI = false, bool SP2 = false>
; __device__ __forceinline__ void gemm_phase(PG8_LAS unsigned char* lds, const Gemm g, const Sched& S, const Epi& E, int tid_in) {
;     ...
;             PG8_LDA(At, 1, 1); PG8_STAGE(PG8_SB(1, 0), b3, voffB); PG8_STAGE(PG8_SB(1, 1), b3 + hstep, voffB); PG8_STAGE(PG8_SA(1, 0), a3, voffA);
;             PG8_WAIT_V(8); PG8_WAIT_L(0); PG8_BAR; PG8_MMA(1, 0, At, B0); PG8_MMA(1, 1, At, B1); PG8_BAR; PG8_SCHED;
;     ...
;         if constexpr (ALIGN_EPI) { if (wr == 0) PG8_BAR; }
	v_mfma_f32_16x16x32_bf16 v[64:67], v[194:197], v[248:251], v[64:67]
	s_setprio 0
	s_mov_b32 m0, s58
	v_lshl_add_u64 v[142:143], v[142:143], 0, s[48:49]
	s_add_u32 s70, s70, 0x40080
	ds_read_b128 v[198:201], v144 offset:49152
	ds_read_b128 v[202:205], v144 offset:50176
	ds_read_b128 v[206:209], v144 offset:51200
	ds_read_b128 v[210:213], v144 offset:52224
	ds_read_b128 v[214:217], v144 offset:53248
	ds_read_b128 v[226:229], v144 offset:54272
	ds_read_b128 v[232:235], v144 offset:55296
	ds_read_b128 v[248:251], v144 offset:56320
	global_load_lds_dwordx4 v[142:143], off
	v_lshl_add_u64 v[142:143], v[176:177], 0, s[48:49]
	s_mov_b32 m0, s59
	s_addc_u32 s71, s71, 0
	global_load_lds_dwordx4 v[142:143], off
	v_lshl_add_u64 v[142:143], s[70:71], 0, v[134:135]
	s_mov_b32 m0, s63
	s_nop 0
	global_load_lds_dwordx4 v[142:143], off
	v_lshl_add_u64 v[142:143], s[70:71], 0, v[130:131]
	s_mov_b32 m0, s67
	s_nop 0
	global_load_lds_dwordx4 v[142:143], off
	v_lshl_add_u64 v[142:143], v[182:183], 0, s[48:49]
	s_mov_b32 m0, s61
	s_nop 0
	global_load_lds_dwordx4 v[142:143], off
	v_lshl_add_u64 v[142:143], v[184:185], 0, s[48:49]
	s_mov_b32 m0, s62
	s_nop 0
	global_load_lds_dwordx4 v[142:143], off
	s_waitcnt vmcnt(8)
	s_waitcnt lgkmcnt(0)
	s_barrier
	s_setprio 1
	s_waitcnt lgkmcnt(0)
	v_mfma_f32_16x16x32_bf16 v[60:63], v[148:151], v[198:201], v[60:63]
	v_mfma_f32_16x16x32_bf16 v[52:55], v[156:159], v[198:201], v[52:55]
	v_mfma_f32_16x16x32_bf16 v[44:47], v[148:151], v[206:209], v[44:47]
	v_mfma_f32_16x16x32_bf16 v[36:39], v[156:159], v[206:209], v[36:39]
	v_mfma_f32_16x16x32_bf16 v[28:31], v[148:151], v[214:217], v[28:31]
	v_mfma_f32_16x16x32_bf16 v[20:23], v[156:159], v[214:217], v[20:23]
	v_mfma_f32_16x16x32_bf16 v[12:15], v[148:151], v[232:235], v[12:15]
	v_mfma_f32_16x16x32_bf16 v[4:7], v[156:159], v[232:235], v[4:7]
	v_mfma_f32_16x16x32_bf16 v[60:63], v[152:155], v[202:205], v[60:63]
	v_mfma_f32_16x16x32_bf16 v[52:55], v[160:163], v[202:205], v[52:55]
	v_mfma_f32_16x16x32_bf16 v[44:47], v[152:155], v[210:213], v[44:47]
	v_mfma_f32_16x16x32_bf16 v[36:39], v[160:163], v[210:213], v[36:39]
	v_mfma_f32_16x16x32_bf16 v[28:31], v[152:155], v[226:229], v[28:31]
	v_mfma_f32_16x16x32_bf16 v[20:23], v[160:163], v[226:229], v[20:23]
	v_mfma_f32_16x16x32_bf16 v[12:15], v[152:155], v[248:251], v[12:15]
	v_mfma_f32_16x16x32_bf16 v[4:7], v[160:163], v[248:251], v[4:7]
	s_setprio 0
	s_setprio 1
	v_mfma_f32_16x16x32_bf16 v[56:59], v[164:167], v[198:201], v[56:59]
	v_mfma_f32_16x16x32_bf16 v[48:51], v[172:175], v[198:201], v[48:51]
	v_mfma_f32_16x16x32_bf16 v[40:43], v[164:167], v[206:209], v[40:43]
	v_mfma_f32_16x16x32_bf16 v[32:35], v[172:175], v[206:209], v[32:35]
	v_mfma_f32_16x16x32_bf16 v[24:27], v[164:167], v[214:217], v[24:27]
	v_mfma_f32_16x16x32_bf16 v[16:19], v[172:175], v[214:217], v[16:19]
	v_mfma_f32_16x16x32_bf16 v[8:11], v[164:167], v[232:235], v[8:11]
	v_mfma_f32_16x16x32_bf16 v[0:3], v[172:175], v[232:235], v[0:3]
	v_mfma_f32_16x16x32_bf16 v[56:59], v[168:171], v[202:205], v[56:59]
	v_mfma_f32_16x16x32_bf16 v[48:51], v[194:197], v[202:205], v[48:51]
	v_mfma_f32_16x16x32_bf16 v[40:43], v[168:171], v[210:213], v[40:43]
	v_mfma_f32_16x16x32_bf16 v[32:35], v[194:197], v[210:213], v[32:35]
	v_mfma_f32_16x16x32_bf16 v[24:27], v[168:171], v[226:229], v[24:27]
	v_mfma_f32_16x16x32_bf16 v[16:19], v[194:197], v[226:229], v[16:19]
	v_mfma_f32_16x16x32_bf16 v[8:11], v[168:171], v[248:251], v[8:11]
	s_barrier
	v_mfma_f32_16x16x32_bf16 v[0:3], v[194:197], v[248:251], v[0:3]
	s_setprio 0
	s_add_i32 s82, s82, 2
	s_add_u32 s68, s68, 0x100
	s_addc_u32 s69, s69, 0
	s_add_u32 s80, s80, 0x100
	s_addc_u32 s81, s81, 0
	s_cmp_gt_u32 s82, 13
	s_cbranch_scc0 .LBB0_780
	s_and_b64 vcc, exec, s[40:41]
	s_cbranch_vccz .Ltrail_783
	s_barrier
	s_branch .LBB0_783
